# meta/pad row LayerNorm (one wave per row): 40 row/partial loads issued in two batches instead of one per vmcnt(0); g/b from LDS
# speedup vs baseline: 1.0034x; 1.0021x over previous
; __device__ __forceinline__ float bf_lo(unsigned w) { return __uint_as_float(w << 16); }
; __device__ __forceinline__ float bf_hi(unsigned w) { return __uint_as_float(w & 0xffff0000u); }
; __device__ __forceinline__ void ln_tail_row(bf16_t* h, const float* part, float scale, const float* g, const float* b, int lane) {
;     f32x4 v[8]; float s = 0.f;
; #pragma unroll
;     for (int j = 0; j < 8; ++j) { const int c = 4 * lane + 256 * j; const u32x2 w = *(const u32x2*)(h + c);
;         f32x4 p = *(const f32x4*)(part + c);
; #pragma unroll
;         for (int q = 1; q < 4; ++q) p = p + *(const f32x4*)(part + (size_t)q * 512 * D + c);
;         const f32x4 h4 = {bf_lo(w.x), bf_hi(w.x), bf_lo(w.y), bf_hi(w.y)};
;         v[j] = h4 * ALPHA + p * scale; s += (v[j].x + v[j].y) + (v[j].z + v[j].w); }
; template <int MODE>
; __device__ __forceinline__ void ln_phase(const Args& a, const float* g, const float* b, int nrows, float scale) {
;     ...
;         for (int r = NTOK + gw; r < nrows; r += NGW) ln_tail_row(hb + (size_t)r * D, (const float*)(a.ws + WS_PART) + (size_t)(r - NTOK) * D, scale, g, b, lane);
.LBB0_91:
	s_or_b64 exec, exec, s[2:3]
	v_readlane_b32 s0, v251, 2
	v_readlane_b32 s1, v251, 3
	s_and_b64 s[0:1], s[0:1], exec
	s_mov_b32 s0, 0xc000
	s_cselect_b32 s0, s0, 0xc200
	v_add_u32_e32 v10, 0xc000, v35
	v_cmp_gt_i32_e32 vcc, s0, v10
	s_and_saveexec_b64 s[2:3], vcc
	v_readlane_b32 s6, v253, 49
	v_readlane_b32 s8, v253, 51
	v_readlane_b32 s40, v253, 58
	v_readlane_b32 s7, v253, 50
	v_readlane_b32 s9, v253, 52
	s_mov_b32 s1, 0x3a866000
	s_mov_b32 s10, 0x3ac66000
	s_mov_b32 s11, 0x3b066000
	s_mov_b32 s12, 0x3b466000
	v_readlane_b32 s46, v254, 0
	v_readlane_b32 s47, v254, 1
	v_readlane_b32 s41, v253, 59
	v_readlane_b32 s42, v253, 60
	v_readlane_b32 s43, v253, 61
	v_readlane_b32 s44, v253, 62
	v_readlane_b32 s45, v253, 63
	s_cbranch_execz .LBB0_94
	v_xor_b32_e32 v1, 1, v201
	v_cmp_lt_i32_e32 vcc, v1, v202
	v_xor_b32_e32 v2, 2, v201
	v_mov_b32_e32 v3, v0
	v_cndmask_b32_e32 v1, v201, v1, vcc
	v_cmp_lt_i32_e32 vcc, v2, v202
	v_ashrrev_i32_e32 v35, 31, v34
	s_ashr_i32 s37, s36, 31
	v_cndmask_b32_e32 v2, v201, v2, vcc
	s_waitcnt vmcnt(0)
	v_lshlrev_b32_e32 v67, 2, v2
	v_xor_b32_e32 v2, 4, v201
	v_cmp_lt_i32_e32 vcc, v2, v202
	v_ashrrev_i32_e32 v11, 31, v10
	v_mov_b32_e32 v37, v0
	v_cndmask_b32_e32 v2, v201, v2, vcc
	v_lshlrev_b32_e32 v72, 2, v2
	v_xor_b32_e32 v2, 8, v201
	v_cmp_lt_i32_e32 vcc, v2, v202
	v_lshlrev_b32_e32 v1, 2, v1
	v_lshl_add_u64 v[12:13], s[20:21], 0, v[36:37]
	v_cndmask_b32_e32 v2, v201, v2, vcc
	v_lshlrev_b32_e32 v73, 2, v2
	v_xor_b32_e32 v2, 16, v201
	v_cmp_lt_i32_e32 vcc, v2, v202
	v_lshl_add_u64 v[14:15], s[30:31], 0, v[36:37]
	s_nop 0
	v_cndmask_b32_e32 v2, v201, v2, vcc
	v_lshlrev_b32_e32 v74, 2, v2
	v_xor_b32_e32 v2, 32, v201
	v_cmp_lt_i32_e32 vcc, v2, v202
	s_nop 1
	v_cndmask_b32_e32 v2, v201, v2, vcc
	v_lshlrev_b32_e32 v75, 2, v2
	v_or_b32_e32 v2, 0x1000, v36
	v_lshl_add_u64 v[16:17], s[20:21], 0, v[2:3]
	v_lshl_add_u64 v[18:19], s[30:31], 0, v[2:3]
	v_or_b32_e32 v2, 0x1400, v36
	v_lshl_add_u64 v[20:21], s[20:21], 0, v[2:3]
	v_lshl_add_u64 v[22:23], s[30:31], 0, v[2:3]
	v_or_b32_e32 v2, 0x1800, v36
	v_lshl_add_u64 v[24:25], s[20:21], 0, v[2:3]
	v_lshl_add_u64 v[26:27], s[30:31], 0, v[2:3]
	v_or_b32_e32 v2, 0x1c00, v36
	v_lshl_add_u64 v[28:29], s[20:21], 0, v[2:3]
	v_lshl_add_u64 v[30:31], s[30:31], 0, v[2:3]
	v_lshl_add_u64 v[2:3], v[34:35], 0, s[36:37]
	v_lshlrev_b64 v[32:33], 13, v[2:3]
	v_lshlrev_b64 v[34:35], 12, v[10:11]
	v_lshl_or_b32 v32, v109, 4, v32
	v_lshl_or_b32 v34, v109, 3, v34
	s_mov_b64 s[20:21], 0
	v_lshlrev_b32_e32 v126, 4, v109
	v_add_u32_e32 v126, 0x20000, v126
.LBB0_93:
	v_lshl_add_u64 v[120:121], s[46:47], 0, v[32:33]
	v_lshl_add_u64 v[122:123], s[46:47], 0, v[34:35]
	v_add_co_u32_e32 v230, vcc, 0x3a865000, v120
	s_nop 1
	v_addc_co_u32_e32 v231, vcc, 0, v121, vcc
	v_add_co_u32_e32 v222, vcc, 0x3a866000, v120
	s_nop 1
	v_addc_co_u32_e32 v223, vcc, 0, v121, vcc
	v_add_co_u32_e32 v232, vcc, 0x3ac65000, v120
	s_nop 1
	v_addc_co_u32_e32 v233, vcc, 0, v121, vcc
	v_add_co_u32_e32 v224, vcc, 0x3ac66000, v120
	s_nop 1
	v_addc_co_u32_e32 v225, vcc, 0, v121, vcc
	v_add_co_u32_e32 v234, vcc, 0x3b065000, v120
	s_nop 1
	v_addc_co_u32_e32 v235, vcc, 0, v121, vcc
	v_add_co_u32_e32 v226, vcc, 0x3b066000, v120
	s_nop 1
	v_addc_co_u32_e32 v227, vcc, 0, v121, vcc
	v_add_co_u32_e32 v236, vcc, 0x3b465000, v120
	s_nop 1
	v_addc_co_u32_e32 v237, vcc, 0, v121, vcc
	v_add_co_u32_e32 v228, vcc, 0x3b466000, v120
	s_nop 1
	v_addc_co_u32_e32 v229, vcc, 0, v121, vcc
	global_load_dwordx2 v[214:215], v[122:123], off
	global_load_dwordx2 v[216:217], v[122:123], off offset:512
	global_load_dwordx2 v[218:219], v[122:123], off offset:1024
	global_load_dwordx2 v[220:221], v[122:123], off offset:1536
	global_load_dwordx4 v[130:133], v[230:231], off
	global_load_dwordx4 v[134:137], v[230:231], off offset:1024
	global_load_dwordx4 v[138:141], v[230:231], off offset:2048
	global_load_dwordx4 v[142:145], v[230:231], off offset:3072
	global_load_dwordx4 v[146:149], v[232:233], off
	global_load_dwordx4 v[150:153], v[232:233], off offset:1024
	global_load_dwordx4 v[160:163], v[232:233], off offset:2048
	global_load_dwordx4 v[164:167], v[232:233], off offset:3072
	global_load_dwordx4 v[170:173], v[234:235], off
	global_load_dwordx4 v[174:177], v[234:235], off offset:1024
	global_load_dwordx4 v[178:181], v[234:235], off offset:2048
	global_load_dwordx4 v[182:185], v[234:235], off offset:3072
	global_load_dwordx4 v[186:189], v[236:237], off
	global_load_dwordx4 v[190:193], v[236:237], off offset:1024
	global_load_dwordx4 v[194:197], v[236:237], off offset:2048
	global_load_dwordx4 v[210:213], v[236:237], off offset:3072
	s_waitcnt vmcnt(0)
; __device__ __forceinline__ float bf_lo(unsigned w) { return __uint_as_float(w << 16); }
; __device__ __forceinline__ float bf_hi(unsigned w) { return __uint_as_float(w & 0xffff0000u); }
; __device__ __forceinline__ void ln_tail_row(bf16_t* h, const float* part, float scale, const float* g, const float* b, int lane) {
;     ...
;     for (int j = 0; j < 8; ++j) { const int c = 4 * lane + 256 * j; const u32x2 w = *(const u32x2*)(h + c);
;         f32x4 p = *(const f32x4*)(part + c);
; #pragma unroll
;         for (int q = 1; q < 4; ++q) p = p + *(const f32x4*)(part + (size_t)q * 512 * D + c);
;         const f32x4 h4 = {bf_lo(w.x), bf_hi(w.x), bf_lo(w.y), bf_hi(w.y)};
;         v[j] = h4 * ALPHA + p * scale; s += (v[j].x + v[j].y) + (v[j].z + v[j].w); }
	v_lshl_add_u64 v[42:43], s[46:47], 0, v[32:33]
	v_add_co_u32_e32 v44, vcc, 0x3a865000, v42
	v_lshl_add_u64 v[36:37], s[46:47], 0, v[34:35]
	s_nop 0
	v_addc_co_u32_e32 v45, vcc, 0, v43, vcc
	v_add_co_u32_e32 v46, vcc, 0x3ac65000, v42
	v_mov_b32_e32 v38, v214
	v_mov_b32_e32 v39, v215
	v_mov_b32_e32 v2, v130
	v_mov_b32_e32 v3, v131
	v_mov_b32_e32 v4, v132
	v_mov_b32_e32 v5, v133
	v_addc_co_u32_e32 v47, vcc, 0, v43, vcc
	v_mov_b32_e32 v6, v146
	v_mov_b32_e32 v7, v147
	v_mov_b32_e32 v8, v148
	v_mov_b32_e32 v9, v149
	v_add_co_u32_e32 v48, vcc, 0x3b065000, v42
	v_add_u32_e32 v10, s26, v10
	s_nop 0
	v_addc_co_u32_e32 v49, vcc, 0, v43, vcc
	v_add_co_u32_e32 v50, vcc, 0x3b465000, v42
	v_lshl_add_u64 v[32:33], v[32:33], 0, s[6:7]
	s_nop 0
	v_addc_co_u32_e32 v51, vcc, 0, v43, vcc
	v_add_co_u32_e32 v76, vcc, s1, v42
	v_lshl_add_u64 v[34:35], v[34:35], 0, s[8:9]
	s_nop 0
	v_addc_co_u32_e32 v77, vcc, 0, v43, vcc
	v_add_co_u32_e32 v78, vcc, s10, v42
	v_pk_add_f32 v[8:9], v[4:5], v[8:9]
	v_pk_add_f32 v[6:7], v[2:3], v[6:7]
	v_mov_b32_e32 v2, v170
	v_mov_b32_e32 v3, v171
	v_mov_b32_e32 v4, v172
	v_mov_b32_e32 v5, v173
	v_addc_co_u32_e32 v79, vcc, 0, v43, vcc
	v_add_co_u32_e32 v80, vcc, s11, v42
	v_pk_add_f32 v[8:9], v[8:9], v[4:5]
	v_pk_add_f32 v[6:7], v[6:7], v[2:3]
	v_mov_b32_e32 v2, v186
	v_mov_b32_e32 v3, v187
	v_mov_b32_e32 v4, v188
	v_mov_b32_e32 v5, v189
	v_addc_co_u32_e32 v81, vcc, 0, v43, vcc
	v_add_co_u32_e32 v82, vcc, s12, v42
	v_pk_add_f32 v[4:5], v[8:9], v[4:5]
	v_pk_add_f32 v[6:7], v[6:7], v[2:3]
	v_lshlrev_b32_e32 v8, 16, v38
	v_and_b32_e32 v9, 0xffff0000, v38
	v_lshlrev_b32_e32 v2, 16, v39
	v_and_b32_e32 v3, 0xffff0000, v39
	v_pk_fma_f32 v[2:3], v[2:3], s[24:25], v[4:5] op_sel_hi:[1,0,1]
	v_pk_fma_f32 v[4:5], v[8:9], s[24:25], v[6:7] op_sel_hi:[1,0,1]
	v_mov_b32_e32 v52, v216
	v_mov_b32_e32 v53, v217
	v_mov_b32_e32 v6, v134
	v_mov_b32_e32 v7, v135
	v_mov_b32_e32 v8, v136
	v_mov_b32_e32 v9, v137
	v_mov_b32_e32 v38, v150
	v_mov_b32_e32 v39, v151
	v_mov_b32_e32 v40, v152
	v_mov_b32_e32 v41, v153
	v_addc_co_u32_e32 v83, vcc, 0, v43, vcc
	v_pk_add_f32 v[40:41], v[8:9], v[40:41]
	v_pk_add_f32 v[38:39], v[6:7], v[38:39]
	v_mov_b32_e32 v6, v174
	v_mov_b32_e32 v7, v175
	v_mov_b32_e32 v8, v176
	v_mov_b32_e32 v9, v177
	v_pk_add_f32 v[40:41], v[40:41], v[8:9]
	v_pk_add_f32 v[38:39], v[38:39], v[6:7]
	v_mov_b32_e32 v6, v190
	v_mov_b32_e32 v7, v191
	v_mov_b32_e32 v8, v192
	v_mov_b32_e32 v9, v193
	v_pk_add_f32 v[6:7], v[38:39], v[6:7]
	v_lshlrev_b32_e32 v38, 16, v52
	v_and_b32_e32 v39, 0xffff0000, v52
	v_pk_add_f32 v[8:9], v[40:41], v[8:9]
	v_lshlrev_b32_e32 v40, 16, v53
	v_and_b32_e32 v41, 0xffff0000, v53
	v_pk_fma_f32 v[64:65], v[38:39], s[24:25], v[6:7] op_sel_hi:[1,0,1]
	v_pk_fma_f32 v[62:63], v[40:41], s[24:25], v[8:9] op_sel_hi:[1,0,1]
	v_mov_b32_e32 v6, v4
	v_mov_b32_e32 v7, v64
	v_mov_b32_e32 v8, v5
	v_mov_b32_e32 v9, v65
	v_pk_add_f32 v[6:7], v[6:7], v[8:9]
	v_mov_b32_e32 v8, v2
	v_mov_b32_e32 v9, v62
	v_mov_b32_e32 v38, v3
	v_mov_b32_e32 v39, v63
	v_pk_add_f32 v[8:9], v[8:9], v[38:39]
	s_nop 0
	v_pk_add_f32 v[6:7], v[6:7], v[8:9]
	s_nop 0
	v_add_f32_e32 v6, 0, v6
	v_add_f32_e32 v68, v6, v7
	v_mov_b32_e32 v52, v218
	v_mov_b32_e32 v53, v219
	v_mov_b32_e32 v6, v138
	v_mov_b32_e32 v7, v139
	v_mov_b32_e32 v8, v140
	v_mov_b32_e32 v9, v141
	v_mov_b32_e32 v38, v160
	v_mov_b32_e32 v39, v161
	v_mov_b32_e32 v40, v162
	v_mov_b32_e32 v41, v163
	v_pk_add_f32 v[40:41], v[8:9], v[40:41]
	v_pk_add_f32 v[38:39], v[6:7], v[38:39]
	v_mov_b32_e32 v6, v178
	v_mov_b32_e32 v7, v179
	v_mov_b32_e32 v8, v180
	v_mov_b32_e32 v9, v181
	v_pk_add_f32 v[40:41], v[40:41], v[8:9]
	v_pk_add_f32 v[38:39], v[38:39], v[6:7]
	v_mov_b32_e32 v6, v194
	v_mov_b32_e32 v7, v195
	v_mov_b32_e32 v8, v196
	v_mov_b32_e32 v9, v197
	v_pk_add_f32 v[8:9], v[40:41], v[8:9]
	v_pk_add_f32 v[6:7], v[38:39], v[6:7]
	v_lshlrev_b32_e32 v38, 16, v52
	v_and_b32_e32 v39, 0xffff0000, v52
	v_lshlrev_b32_e32 v40, 16, v53
	v_and_b32_e32 v41, 0xffff0000, v53
	v_pk_fma_f32 v[58:59], v[40:41], s[24:25], v[8:9] op_sel_hi:[1,0,1]
	v_pk_fma_f32 v[60:61], v[38:39], s[24:25], v[6:7] op_sel_hi:[1,0,1]
	v_mov_b32_e32 v9, v59
	v_pk_mov_b32 v[6:7], v[60:61], v[58:59] op_sel:[1,0]
	v_mov_b32_e32 v8, v60
	v_pk_add_f32 v[6:7], v[6:7], v[8:9]
	s_nop 0
	v_pk_add_f32 v[70:71], v[6:7], v[6:7] op_sel:[0,1] op_sel_hi:[1,0]
	v_mov_b32_e32 v52, v220
	v_mov_b32_e32 v53, v221
	v_mov_b32_e32 v6, v142
	v_mov_b32_e32 v7, v143
	v_mov_b32_e32 v8, v144
	v_mov_b32_e32 v9, v145
	v_mov_b32_e32 v38, v164
	v_mov_b32_e32 v39, v165
	v_mov_b32_e32 v40, v166
	v_mov_b32_e32 v41, v167
	v_pk_add_f32 v[40:41], v[8:9], v[40:41]
	v_pk_add_f32 v[38:39], v[6:7], v[38:39]
	v_mov_b32_e32 v6, v182
	v_mov_b32_e32 v7, v183
	v_mov_b32_e32 v8, v184
	v_mov_b32_e32 v9, v185
	v_pk_add_f32 v[40:41], v[40:41], v[8:9]
	v_pk_add_f32 v[38:39], v[38:39], v[6:7]
	v_mov_b32_e32 v6, v210
	v_mov_b32_e32 v7, v211
	v_mov_b32_e32 v8, v212
	v_mov_b32_e32 v9, v213
	global_load_dwordx2 v[214:215], v[122:123], off offset:2048
	global_load_dwordx2 v[216:217], v[122:123], off offset:2560
	global_load_dwordx2 v[218:219], v[122:123], off offset:3072
	global_load_dwordx2 v[220:221], v[122:123], off offset:3584
	global_load_dwordx4 v[130:133], v[222:223], off
	global_load_dwordx4 v[134:137], v[222:223], off offset:1024
	global_load_dwordx4 v[138:141], v[222:223], off offset:2048
	global_load_dwordx4 v[142:145], v[222:223], off offset:3072
	global_load_dwordx4 v[146:149], v[224:225], off
	global_load_dwordx4 v[150:153], v[224:225], off offset:1024
	global_load_dwordx4 v[160:163], v[224:225], off offset:2048
	global_load_dwordx4 v[164:167], v[224:225], off offset:3072
	global_load_dwordx4 v[170:173], v[226:227], off
	global_load_dwordx4 v[174:177], v[226:227], off offset:1024
	global_load_dwordx4 v[178:181], v[226:227], off offset:2048
	global_load_dwordx4 v[182:185], v[226:227], off offset:3072
	global_load_dwordx4 v[186:189], v[228:229], off
	global_load_dwordx4 v[190:193], v[228:229], off offset:1024
	global_load_dwordx4 v[194:197], v[228:229], off offset:2048
	global_load_dwordx4 v[210:213], v[228:229], off offset:3072
	s_waitcnt vmcnt(0)
; __device__ __forceinline__ float bf_lo(unsigned w) { return __uint_as_float(w << 16); }
; __device__ __forceinline__ float bf_hi(unsigned w) { return __uint_as_float(w & 0xffff0000u); }
; __device__ __forceinline__ void ln_tail_row(bf16_t* h, const float* part, float scale, const float* g, const float* b, int lane) {
;     ...
;     for (int j = 0; j < 8; ++j) { const int c = 4 * lane + 256 * j; const u32x2 w = *(const u32x2*)(h + c);
;         f32x4 p = *(const f32x4*)(part + c);
; #pragma unroll
;         for (int q = 1; q < 4; ++q) p = p + *(const f32x4*)(part + (size_t)q * 512 * D + c);
;         const f32x4 h4 = {bf_lo(w.x), bf_hi(w.x), bf_lo(w.y), bf_hi(w.y)};
;         v[j] = h4 * ALPHA + p * scale; s += (v[j].x + v[j].y) + (v[j].z + v[j].w); }
;     const float mean = wave_sum(s) * (1.f / D); float s2 = 0.f;
	v_mov_b32_e32 v48, v214
	v_mov_b32_e32 v49, v215
	v_pk_add_f32 v[8:9], v[40:41], v[8:9]
	v_pk_add_f32 v[6:7], v[38:39], v[6:7]
	v_lshlrev_b32_e32 v38, 16, v52
	v_and_b32_e32 v39, 0xffff0000, v52
	v_lshlrev_b32_e32 v40, 16, v53
	v_and_b32_e32 v41, 0xffff0000, v53
	v_pk_fma_f32 v[54:55], v[40:41], s[24:25], v[8:9] op_sel_hi:[1,0,1]
	v_pk_fma_f32 v[56:57], v[38:39], s[24:25], v[6:7] op_sel_hi:[1,0,1]
	v_mov_b32_e32 v6, v130
	v_mov_b32_e32 v7, v131
	v_mov_b32_e32 v8, v132
	v_mov_b32_e32 v9, v133
	v_mov_b32_e32 v38, v146
	v_mov_b32_e32 v39, v147
	v_mov_b32_e32 v40, v148
	v_mov_b32_e32 v41, v149
	v_add_f32_e32 v44, v56, v57
	v_add_f32_e32 v46, v54, v55
	v_pk_add_f32 v[40:41], v[8:9], v[40:41]
	v_pk_add_f32 v[38:39], v[6:7], v[38:39]
	v_mov_b32_e32 v6, v170
	v_mov_b32_e32 v7, v171
	v_mov_b32_e32 v8, v172
	v_mov_b32_e32 v9, v173
	v_pk_add_f32 v[40:41], v[40:41], v[8:9]
	v_pk_add_f32 v[38:39], v[38:39], v[6:7]
	v_mov_b32_e32 v6, v186
	v_mov_b32_e32 v7, v187
	v_mov_b32_e32 v8, v188
	v_mov_b32_e32 v9, v189
	v_pk_add_f32 v[8:9], v[40:41], v[8:9]
	v_pk_add_f32 v[6:7], v[38:39], v[6:7]
	v_lshlrev_b32_e32 v38, 16, v48
	v_and_b32_e32 v39, 0xffff0000, v48
	v_lshlrev_b32_e32 v40, 16, v49
	v_and_b32_e32 v41, 0xffff0000, v49
	v_pk_fma_f32 v[50:51], v[40:41], s[24:25], v[8:9] op_sel_hi:[1,0,1]
	v_pk_fma_f32 v[52:53], v[38:39], s[24:25], v[6:7] op_sel_hi:[1,0,1]
	v_mov_b32_e32 v45, v50
	v_mov_b32_e32 v69, v52
	v_mov_b32_e32 v71, v53
	v_mov_b32_e32 v47, v51
	v_pk_add_f32 v[6:7], v[68:69], v[70:71]
	v_pk_add_f32 v[8:9], v[44:45], v[46:47]
	s_nop 0
	v_pk_add_f32 v[6:7], v[6:7], v[8:9]
	s_nop 0
	v_pk_add_f32 v[68:69], v[6:7], v[6:7] op_sel:[0,1] op_sel_hi:[1,0]
	v_mov_b32_e32 v42, v216
	v_mov_b32_e32 v43, v217
	v_mov_b32_e32 v6, v134
	v_mov_b32_e32 v7, v135
	v_mov_b32_e32 v8, v136
	v_mov_b32_e32 v9, v137
	v_mov_b32_e32 v38, v150
	v_mov_b32_e32 v39, v151
	v_mov_b32_e32 v40, v152
	v_mov_b32_e32 v41, v153
	v_pk_add_f32 v[40:41], v[8:9], v[40:41]
	v_pk_add_f32 v[38:39], v[6:7], v[38:39]
	v_mov_b32_e32 v6, v174
	v_mov_b32_e32 v7, v175
	v_mov_b32_e32 v8, v176
	v_mov_b32_e32 v9, v177
	v_pk_add_f32 v[40:41], v[40:41], v[8:9]
	v_pk_add_f32 v[38:39], v[38:39], v[6:7]
	v_mov_b32_e32 v6, v190
	v_mov_b32_e32 v7, v191
	v_mov_b32_e32 v8, v192
	v_mov_b32_e32 v9, v193
	v_pk_add_f32 v[8:9], v[40:41], v[8:9]
	v_pk_add_f32 v[6:7], v[38:39], v[6:7]
	v_lshlrev_b32_e32 v38, 16, v42
	v_and_b32_e32 v39, 0xffff0000, v42
	v_lshlrev_b32_e32 v40, 16, v43
	v_and_b32_e32 v41, 0xffff0000, v43
	v_pk_fma_f32 v[46:47], v[40:41], s[24:25], v[8:9] op_sel_hi:[1,0,1]
	v_pk_fma_f32 v[48:49], v[38:39], s[24:25], v[6:7] op_sel_hi:[1,0,1]
	v_mov_b32_e32 v9, v47
	v_pk_mov_b32 v[6:7], v[48:49], v[46:47] op_sel:[1,0]
	v_mov_b32_e32 v8, v48
	v_pk_add_f32 v[6:7], v[6:7], v[8:9]
	s_nop 0
	v_pk_add_f32 v[70:71], v[6:7], v[6:7] op_sel:[0,1] op_sel_hi:[1,0]
	v_mov_b32_e32 v42, v218
	v_mov_b32_e32 v43, v219
	v_mov_b32_e32 v6, v138
	v_mov_b32_e32 v7, v139
	v_mov_b32_e32 v8, v140
	v_mov_b32_e32 v9, v141
	v_mov_b32_e32 v38, v160
	v_mov_b32_e32 v39, v161
	v_mov_b32_e32 v40, v162
	v_mov_b32_e32 v41, v163
	v_pk_add_f32 v[40:41], v[8:9], v[40:41]
	v_pk_add_f32 v[38:39], v[6:7], v[38:39]
	v_mov_b32_e32 v6, v178
	v_mov_b32_e32 v7, v179
	v_mov_b32_e32 v8, v180
	v_mov_b32_e32 v9, v181
	v_pk_add_f32 v[40:41], v[40:41], v[8:9]
	v_pk_add_f32 v[38:39], v[38:39], v[6:7]
	v_mov_b32_e32 v6, v194
	v_mov_b32_e32 v7, v195
	v_mov_b32_e32 v8, v196
	v_mov_b32_e32 v9, v197
	v_pk_add_f32 v[8:9], v[40:41], v[8:9]
	v_pk_add_f32 v[6:7], v[38:39], v[6:7]
	v_lshlrev_b32_e32 v38, 16, v42
	v_and_b32_e32 v39, 0xffff0000, v42
	v_lshlrev_b32_e32 v40, 16, v43
	v_and_b32_e32 v41, 0xffff0000, v43
	v_pk_fma_f32 v[42:43], v[40:41], s[24:25], v[8:9] op_sel_hi:[1,0,1]
	v_pk_fma_f32 v[44:45], v[38:39], s[24:25], v[6:7] op_sel_hi:[1,0,1]
	v_mov_b32_e32 v88, v220
	v_mov_b32_e32 v89, v221
	v_mov_b32_e32 v6, v142
	v_mov_b32_e32 v7, v143
	v_mov_b32_e32 v8, v144
	v_mov_b32_e32 v9, v145
	v_mov_b32_e32 v38, v164
	v_mov_b32_e32 v39, v165
	v_mov_b32_e32 v40, v166
	v_mov_b32_e32 v41, v167
	v_add_f32_e32 v84, v44, v45
	v_add_f32_e32 v86, v42, v43
	v_pk_add_f32 v[40:41], v[8:9], v[40:41]
	v_pk_add_f32 v[38:39], v[6:7], v[38:39]
	v_mov_b32_e32 v6, v182
	v_mov_b32_e32 v7, v183
	v_mov_b32_e32 v8, v184
	v_mov_b32_e32 v9, v185
	v_pk_add_f32 v[40:41], v[40:41], v[8:9]
	v_pk_add_f32 v[38:39], v[38:39], v[6:7]
	v_mov_b32_e32 v6, v210
	v_mov_b32_e32 v7, v211
	v_mov_b32_e32 v8, v212
	v_mov_b32_e32 v9, v213
	v_pk_add_f32 v[8:9], v[40:41], v[8:9]
	v_pk_add_f32 v[6:7], v[38:39], v[6:7]
	v_lshlrev_b32_e32 v40, 16, v88
	v_and_b32_e32 v41, 0xffff0000, v88
	v_lshlrev_b32_e32 v38, 16, v89
	v_and_b32_e32 v39, 0xffff0000, v89
	v_pk_fma_f32 v[38:39], v[38:39], s[24:25], v[8:9] op_sel_hi:[1,0,1]
	v_pk_fma_f32 v[40:41], v[40:41], s[24:25], v[6:7] op_sel_hi:[1,0,1]
	v_mov_b32_e32 v85, v38
	v_mov_b32_e32 v69, v40
	v_mov_b32_e32 v71, v41
	v_mov_b32_e32 v87, v39
	v_pk_add_f32 v[6:7], v[68:69], v[70:71]
	v_pk_add_f32 v[8:9], v[84:85], v[86:87]
	s_nop 0
	v_pk_add_f32 v[6:7], v[6:7], v[8:9]
	s_nop 0
	v_add_f32_e32 v6, v6, v7
	ds_bpermute_b32 v7, v1, v6
	s_waitcnt lgkmcnt(0)
	v_add_f32_e32 v6, v6, v7
	ds_bpermute_b32 v7, v67, v6
	s_waitcnt lgkmcnt(0)
	v_add_f32_e32 v6, v6, v7
	ds_bpermute_b32 v7, v72, v6
	s_waitcnt lgkmcnt(0)
	v_add_f32_e32 v6, v6, v7
	ds_bpermute_b32 v7, v73, v6
	s_waitcnt lgkmcnt(0)
	v_add_f32_e32 v6, v6, v7
	ds_bpermute_b32 v7, v74, v6
	s_waitcnt lgkmcnt(0)
	v_add_f32_e32 v6, v6, v7
	ds_bpermute_b32 v7, v75, v6
	s_waitcnt lgkmcnt(0)
; __device__ __forceinline__ void ln_tail_row(bf16_t* h, const float* part, float scale, const float* g, const float* b, int lane) {
;     ...
;     const float mean = wave_sum(s) * (1.f / D); float s2 = 0.f;
; #pragma unroll
;     for (int j = 0; j < 8; ++j) { v[j] = v[j] - mean; s2 += (v[j].x * v[j].x + v[j].y * v[j].y) + (v[j].z * v[j].z + v[j].w * v[j].w); }
;     const float rstd = rsqrtf(wave_sum(s2) * (1.f / D) + LN_EPS);
	v_add_f32_e32 v11, v6, v7
	v_fmamk_f32 v5, v11, 0xba000000, v5
	v_fmamk_f32 v65, v11, 0xba000000, v65
	v_fmamk_f32 v3, v11, 0xba000000, v3
	v_fmac_f32_e32 v4, 0xba000000, v11
	v_fmamk_f32 v63, v11, 0xba000000, v63
	v_fmac_f32_e32 v64, 0xba000000, v11
	v_mov_b32_e32 v8, v5
	v_mov_b32_e32 v9, v65
	v_fmac_f32_e32 v2, 0xba000000, v11
	v_fmac_f32_e32 v62, 0xba000000, v11
	v_mov_b32_e32 v6, v4
	v_mov_b32_e32 v7, v64
	v_pk_mul_f32 v[8:9], v[8:9], v[8:9]
	v_mov_b32_e32 v68, v3
	v_mov_b32_e32 v69, v63
	v_pk_fma_f32 v[6:7], v[6:7], v[6:7], v[8:9]
	v_mov_b32_e32 v8, v2
	v_mov_b32_e32 v9, v62
	v_pk_mul_f32 v[68:69], v[68:69], v[68:69]
	v_fmamk_f32 v61, v11, 0xba000000, v61
	v_pk_fma_f32 v[8:9], v[8:9], v[8:9], v[68:69]
	v_fmac_f32_e32 v60, 0xba000000, v11
	v_pk_add_f32 v[6:7], v[6:7], v[8:9]
	v_fmamk_f32 v59, v11, 0xba000000, v59
	v_fmac_f32_e32 v58, 0xba000000, v11
	v_pk_add_f32 v[6:7], v[6:7], v[6:7] op_sel_hi:[0,1]
	v_pk_mul_f32 v[8:9], v[58:59], v[58:59]
	v_pk_mul_f32 v[68:69], v[60:61], v[60:61]
	v_fmac_f32_e32 v56, 0xba000000, v11
	v_pk_mov_b32 v[70:71], v[68:69], v[8:9] op_sel:[1,0]
	v_mov_b32_e32 v69, v9
	v_fmamk_f32 v57, v11, 0xba000000, v57
	v_fmac_f32_e32 v54, 0xba000000, v11
	v_mul_f32_e32 v6, v56, v56
	v_pk_add_f32 v[8:9], v[70:71], v[68:69]
	v_fmamk_f32 v55, v11, 0xba000000, v55
	v_pk_fma_f32 v[68:69], v[56:57], v[56:57], v[6:7] op_sel_hi:[1,1,0]
	v_mul_f32_e32 v6, v54, v54
	v_pk_add_f32 v[8:9], v[8:9], v[8:9] op_sel_hi:[0,1]
	v_pk_fma_f32 v[70:71], v[54:55], v[54:55], v[6:7] op_sel_hi:[1,1,0]
	v_fmamk_f32 v51, v11, 0xba000000, v51
	v_fmac_f32_e32 v50, 0xba000000, v11
	v_fmamk_f32 v53, v11, 0xba000000, v53
	v_fmac_f32_e32 v52, 0xba000000, v11
	v_mul_f32_e32 v68, v52, v52
	v_mul_f32_e32 v70, v53, v53
	v_mul_f32_e32 v8, v50, v50
	v_mul_f32_e32 v6, v51, v51
	v_pk_add_f32 v[68:69], v[68:69], v[70:71]
	v_pk_add_f32 v[6:7], v[8:9], v[6:7]
	v_fmamk_f32 v49, v11, 0xba000000, v49
	v_pk_add_f32 v[6:7], v[68:69], v[6:7]
	v_fmac_f32_e32 v48, 0xba000000, v11
	v_fmamk_f32 v47, v11, 0xba000000, v47
	v_fmac_f32_e32 v46, 0xba000000, v11
	v_pk_add_f32 v[6:7], v[6:7], v[6:7] op_sel_hi:[0,1]
	v_pk_mul_f32 v[8:9], v[46:47], v[46:47]
	v_pk_mul_f32 v[68:69], v[48:49], v[48:49]
	v_fmac_f32_e32 v44, 0xba000000, v11
	v_pk_mov_b32 v[70:71], v[68:69], v[8:9] op_sel:[1,0]
	v_mov_b32_e32 v69, v9
	v_fmamk_f32 v45, v11, 0xba000000, v45
	v_fmac_f32_e32 v42, 0xba000000, v11
	v_mul_f32_e32 v6, v44, v44
	v_pk_add_f32 v[8:9], v[70:71], v[68:69]
	v_fmamk_f32 v43, v11, 0xba000000, v43
	v_pk_fma_f32 v[68:69], v[44:45], v[44:45], v[6:7] op_sel_hi:[1,1,0]
	v_mul_f32_e32 v6, v42, v42
	v_pk_add_f32 v[8:9], v[8:9], v[8:9] op_sel_hi:[0,1]
	v_pk_fma_f32 v[70:71], v[42:43], v[42:43], v[6:7] op_sel_hi:[1,1,0]
	v_fmamk_f32 v39, v11, 0xba000000, v39
	v_fmac_f32_e32 v38, 0xba000000, v11
	v_fmamk_f32 v41, v11, 0xba000000, v41
	v_fmac_f32_e32 v40, 0xba000000, v11
	v_mul_f32_e32 v68, v40, v40
	v_mul_f32_e32 v70, v41, v41
	v_mul_f32_e32 v8, v38, v38
	v_mul_f32_e32 v6, v39, v39
	v_pk_add_f32 v[68:69], v[68:69], v[70:71]
	v_pk_add_f32 v[6:7], v[8:9], v[6:7]
	s_nop 0
	v_pk_add_f32 v[6:7], v[68:69], v[6:7]
	s_nop 0
	v_add_f32_e32 v6, v6, v7
	ds_bpermute_b32 v7, v1, v6
	s_waitcnt lgkmcnt(0)
	v_add_f32_e32 v6, v6, v7
	ds_bpermute_b32 v7, v67, v6
	s_waitcnt lgkmcnt(0)
	v_add_f32_e32 v6, v6, v7
	ds_bpermute_b32 v7, v72, v6
	s_waitcnt lgkmcnt(0)
	v_add_f32_e32 v6, v6, v7
	ds_bpermute_b32 v7, v73, v6
	s_waitcnt lgkmcnt(0)
	v_add_f32_e32 v6, v6, v7
	ds_bpermute_b32 v7, v74, v6
	s_waitcnt lgkmcnt(0)
	v_add_f32_e32 v6, v6, v7
	ds_bpermute_b32 v7, v75, v6
	s_waitcnt lgkmcnt(0)
; __device__ __forceinline__ unsigned cvt_pk_bf16(float lo, float hi) { unsigned r; asm volatile("v_cvt_pk_bf16_f32 %0, %1, %2" : "=v"(r) : "v"(lo), "v"(hi)); return r; }
; __device__ __forceinline__ void ln_tail_row(bf16_t* h, const float* part, float scale, const float* g, const float* b, int lane) {
;     ...
;     const float rstd = rsqrtf(wave_sum(s2) * (1.f / D) + LN_EPS);
; #pragma unroll
;     for (int j = 0; j < 8; ++j) { const int c = 4 * lane + 256 * j; const f32x4 y = v[j] * rstd * *(const f32x4*)(g + c) + *(const f32x4*)(b + c);
;         u32x2 w; w.x = cvt_pk_bf16(y.x, y.y); w.y = cvt_pk_bf16(y.z, y.w); *(u32x2*)(h + c) = w; }
	v_add_f32_e32 v6, v6, v7
	v_fmamk_f32 v6, v6, 0x3a000000, v154
	v_cmp_gt_f32_e32 vcc, s73, v6
	v_mul_f32_e32 v7, 0x4b800000, v6
	s_nop 0
	v_cndmask_b32_e32 v6, v6, v7, vcc
	v_rsq_f32_e32 v6, v6
	s_nop 0
	v_mul_f32_e32 v7, 0x45800000, v6
	v_cndmask_b32_e32 v66, v6, v7, vcc
	v_pk_mul_f32 v[68:69], v[4:5], v[66:67] op_sel_hi:[1,0]
	v_pk_mul_f32 v[70:71], v[2:3], v[66:67] op_sel_hi:[1,0]
	ds_read_b128 v[2:5], v126
	ds_read_b128 v[6:9], v126 offset:8192
	v_pk_mul_f32 v[64:65], v[64:65], v[66:67] op_sel_hi:[1,0]
	v_pk_mul_f32 v[62:63], v[62:63], v[66:67] op_sel_hi:[1,0]
	v_pk_mul_f32 v[60:61], v[60:61], v[66:67] op_sel_hi:[1,0]
	v_pk_mul_f32 v[58:59], v[58:59], v[66:67] op_sel_hi:[1,0]
	v_pk_mul_f32 v[56:57], v[56:57], v[66:67] op_sel_hi:[1,0]
	v_pk_mul_f32 v[54:55], v[54:55], v[66:67] op_sel_hi:[1,0]
	v_pk_mul_f32 v[52:53], v[52:53], v[66:67] op_sel_hi:[1,0]
	v_pk_mul_f32 v[50:51], v[50:51], v[66:67] op_sel_hi:[1,0]
	v_pk_mul_f32 v[48:49], v[48:49], v[66:67] op_sel_hi:[1,0]
	v_pk_mul_f32 v[46:47], v[46:47], v[66:67] op_sel_hi:[1,0]
	v_pk_mul_f32 v[44:45], v[44:45], v[66:67] op_sel_hi:[1,0]
	v_pk_mul_f32 v[42:43], v[42:43], v[66:67] op_sel_hi:[1,0]
	v_pk_mul_f32 v[40:41], v[40:41], v[66:67] op_sel_hi:[1,0]
	v_cmp_le_i32_e32 vcc, s0, v10
	v_pk_mul_f32 v[38:39], v[38:39], v[66:67] op_sel_hi:[1,0]
	s_or_b64 s[20:21], vcc, s[20:21]
	s_waitcnt lgkmcnt(0)
	v_pk_fma_f32 v[2:3], v[2:3], v[68:69], v[6:7]
	v_pk_fma_f32 v[4:5], v[4:5], v[70:71], v[8:9]
	v_cvt_pk_bf16_f32 v2, v2, v3
	s_nop 0
	v_cvt_pk_bf16_f32 v3, v4, v5
	global_store_dwordx2 v[36:37], v[2:3], off
	s_nop 1
	ds_read_b128 v[2:5], v126 offset:1024
	s_nop 0
	ds_read_b128 v[6:9], v126 offset:9216
	s_waitcnt lgkmcnt(0)
	v_pk_fma_f32 v[2:3], v[2:3], v[64:65], v[6:7]
	v_pk_fma_f32 v[4:5], v[4:5], v[62:63], v[8:9]
	v_cvt_pk_bf16_f32 v2, v2, v3
	s_nop 0
	v_cvt_pk_bf16_f32 v3, v4, v5
	global_store_dwordx2 v[36:37], v[2:3], off offset:512
	s_nop 1
	ds_read_b128 v[2:5], v126 offset:2048
	s_nop 0
	ds_read_b128 v[6:9], v126 offset:10240
	s_waitcnt lgkmcnt(0)
	v_pk_fma_f32 v[2:3], v[2:3], v[60:61], v[6:7]
	v_pk_fma_f32 v[4:5], v[4:5], v[58:59], v[8:9]
	v_cvt_pk_bf16_f32 v2, v2, v3
	s_nop 0
	v_cvt_pk_bf16_f32 v3, v4, v5
	global_store_dwordx2 v[36:37], v[2:3], off offset:1024
	s_nop 1
	ds_read_b128 v[2:5], v126 offset:3072
	s_nop 0
	ds_read_b128 v[6:9], v126 offset:11264
	s_waitcnt lgkmcnt(0)
	v_pk_fma_f32 v[2:3], v[2:3], v[56:57], v[6:7]
	v_pk_fma_f32 v[4:5], v[4:5], v[54:55], v[8:9]
	v_cvt_pk_bf16_f32 v2, v2, v3
	s_nop 0
	v_cvt_pk_bf16_f32 v3, v4, v5
	global_store_dwordx2 v[36:37], v[2:3], off offset:1536
	s_nop 1
	ds_read_b128 v[2:5], v126 offset:4096
	s_nop 0
	ds_read_b128 v[6:9], v126 offset:12288
	s_waitcnt lgkmcnt(0)
	v_pk_fma_f32 v[2:3], v[2:3], v[52:53], v[6:7]
	v_pk_fma_f32 v[4:5], v[4:5], v[50:51], v[8:9]
	v_cvt_pk_bf16_f32 v2, v2, v3
	s_nop 0
	v_cvt_pk_bf16_f32 v3, v4, v5
	global_store_dwordx2 v[36:37], v[2:3], off offset:2048
	s_nop 1
	ds_read_b128 v[2:5], v126 offset:5120
	s_nop 0
	ds_read_b128 v[6:9], v126 offset:13312
	s_waitcnt lgkmcnt(0)
	v_pk_fma_f32 v[2:3], v[2:3], v[48:49], v[6:7]
	v_pk_fma_f32 v[4:5], v[4:5], v[46:47], v[8:9]
	v_cvt_pk_bf16_f32 v2, v2, v3
	s_nop 0
	v_cvt_pk_bf16_f32 v3, v4, v5
	global_store_dwordx2 v[36:37], v[2:3], off offset:2560
	s_nop 1
	ds_read_b128 v[2:5], v126 offset:6144
	s_nop 0
	ds_read_b128 v[6:9], v126 offset:14336
	s_waitcnt lgkmcnt(0)
	v_pk_fma_f32 v[2:3], v[2:3], v[44:45], v[6:7]
	v_pk_fma_f32 v[4:5], v[4:5], v[42:43], v[8:9]
	v_cvt_pk_bf16_f32 v2, v2, v3
	s_nop 0
	v_cvt_pk_bf16_f32 v3, v4, v5
	global_store_dwordx2 v[36:37], v[2:3], off offset:3072
	s_nop 1
	ds_read_b128 v[2:5], v126 offset:7168
	s_nop 0
	ds_read_b128 v[6:9], v126 offset:15360
	s_waitcnt lgkmcnt(0)
	v_pk_fma_f32 v[2:3], v[40:41], v[2:3], v[6:7]
	v_pk_fma_f32 v[4:5], v[38:39], v[4:5], v[8:9]
	v_cvt_pk_bf16_f32 v2, v2, v3
	s_nop 0
	v_cvt_pk_bf16_f32 v3, v4, v5
	global_store_dwordx2 v[36:37], v[2:3], off offset:3584
	s_andn2_b64 exec, exec, s[20:21]
	s_cbranch_execnz .LBB0_93

; __device__ __forceinline__ float bf_lo(unsigned w) { return __uint_as_float(w << 16); }
; __device__ __forceinline__ float bf_hi(unsigned w) { return __uint_as_float(w & 0xffff0000u); }
; __device__ __forceinline__ void ln_tail_row(bf16_t* h, const float* part, float scale, const float* g, const float* b, int lane) {
;     f32x4 v[8]; float s = 0.f;
; #pragma unroll
;     for (int j = 0; j < 8; ++j) { const int c = 4 * lane + 256 * j; const u32x2 w = *(const u32x2*)(h + c);
;         f32x4 p = *(const f32x4*)(part + c);
; #pragma unroll
;         for (int q = 1; q < 4; ++q) p = p + *(const f32x4*)(part + (size_t)q * 512 * D + c);
;         const f32x4 h4 = {bf_lo(w.x), bf_hi(w.x), bf_lo(w.y), bf_hi(w.y)};
;         v[j] = h4 * ALPHA + p * scale; s += (v[j].x + v[j].y) + (v[j].z + v[j].w); }
; template <int MODE>
; __device__ __forceinline__ void ln_phase(const Args& a, const float* g, const float* b, int nrows, float scale) {
;     ...
;         for (int r = NTOK + gw; r < nrows; r += NGW) ln_tail_row(hb + (size_t)r * D, (const float*)(a.ws + WS_PART) + (size_t)(r - NTOK) * D, scale, g, b, lane);
.LBB0_348:
	s_or_b64 exec, exec, s[92:93]
	s_mov_b64 s[30:31], s[94:95]
	s_movk_i32 s0, 0x200
	v_cmp_gt_i32_e32 vcc, s0, v43
	s_mov_b64 s[2:3], exec
	v_readlane_b32 s4, v253, 49
	v_readlane_b32 s6, v253, 51
	v_readlane_b32 s52, v254, 47
	v_readlane_b32 s88, v253, 58
	s_and_b64 s[0:1], s[2:3], vcc
	v_readlane_b32 s5, v253, 50
	v_readlane_b32 s7, v253, 52
	s_mov_b32 s8, 0x3a866000
	s_mov_b32 s9, 0x3ac66000
	s_mov_b32 s10, 0x3b066000
	s_mov_b32 s11, 0x3b466000
	s_mov_b32 s12, 0xc1ff
	v_readlane_b32 s53, v254, 48
	v_readlane_b32 s54, v254, 49
	v_readlane_b32 s55, v254, 50
	v_readlane_b32 s56, v254, 51
	v_readlane_b32 s57, v254, 52
	v_readlane_b32 s58, v254, 53
	v_readlane_b32 s59, v254, 54
	v_readlane_b32 s60, v254, 55
	v_readlane_b32 s61, v254, 56
	v_readlane_b32 s62, v254, 57
	v_readlane_b32 s63, v254, 58
	v_readlane_b32 s64, v254, 59
	v_readlane_b32 s65, v254, 60
	v_readlane_b32 s66, v254, 61
	v_readlane_b32 s67, v254, 62
	v_readlane_b32 s94, v254, 0
	v_readlane_b32 s95, v254, 1
	v_readlane_b32 s89, v253, 59
	v_readlane_b32 s90, v253, 60
	v_readlane_b32 s91, v253, 61
	v_readlane_b32 s92, v253, 62
	v_readlane_b32 s93, v253, 63
	s_mov_b64 exec, s[0:1]
	s_cbranch_execz .LBB0_351
	v_xor_b32_e32 v1, 1, v201
	v_cmp_lt_i32_e32 vcc, v1, v202
	v_xor_b32_e32 v2, 2, v201
	v_mov_b32_e32 v3, v0
	v_cndmask_b32_e32 v1, v201, v1, vcc
	v_cmp_lt_i32_e32 vcc, v2, v202
	v_add_u32_e32 v10, 0xc000, v43
	v_ashrrev_i32_e32 v43, 31, v42
	v_cndmask_b32_e32 v2, v201, v2, vcc
	s_waitcnt vmcnt(0)
	v_lshlrev_b32_e32 v67, 2, v2
	v_xor_b32_e32 v2, 4, v201
	v_cmp_lt_i32_e32 vcc, v2, v202
	s_ashr_i32 s47, s46, 31
	v_ashrrev_i32_e32 v11, 31, v10
	v_cndmask_b32_e32 v2, v201, v2, vcc
	v_lshlrev_b32_e32 v72, 2, v2
	v_xor_b32_e32 v2, 8, v201
	v_cmp_lt_i32_e32 vcc, v2, v202
	v_mov_b32_e32 v45, v0
	v_lshlrev_b64 v[34:35], 12, v[10:11]
	v_cndmask_b32_e32 v2, v201, v2, vcc
	v_lshlrev_b32_e32 v73, 2, v2
	v_xor_b32_e32 v2, 16, v201
	v_cmp_lt_i32_e32 vcc, v2, v202
	v_lshlrev_b32_e32 v1, 2, v1
	v_lshl_add_u64 v[12:13], s[42:43], 0, v[44:45]
	v_cndmask_b32_e32 v2, v201, v2, vcc
	v_lshlrev_b32_e32 v74, 2, v2
	v_xor_b32_e32 v2, 32, v201
	v_cmp_lt_i32_e32 vcc, v2, v202
	v_lshl_add_u64 v[14:15], s[44:45], 0, v[44:45]
	v_lshl_or_b32 v34, v109, 3, v34
	v_cndmask_b32_e32 v2, v201, v2, vcc
	v_lshlrev_b32_e32 v75, 2, v2
	v_or_b32_e32 v2, 0x1000, v44
	v_lshl_add_u64 v[16:17], s[42:43], 0, v[2:3]
	v_lshl_add_u64 v[18:19], s[44:45], 0, v[2:3]
	v_or_b32_e32 v2, 0x1400, v44
	v_lshl_add_u64 v[20:21], s[42:43], 0, v[2:3]
	v_lshl_add_u64 v[22:23], s[44:45], 0, v[2:3]
	v_or_b32_e32 v2, 0x1800, v44
	v_lshl_add_u64 v[24:25], s[42:43], 0, v[2:3]
	v_lshl_add_u64 v[26:27], s[44:45], 0, v[2:3]
	v_or_b32_e32 v2, 0x1c00, v44
	v_lshl_add_u64 v[28:29], s[42:43], 0, v[2:3]
	v_lshl_add_u64 v[30:31], s[44:45], 0, v[2:3]
	v_lshl_add_u64 v[2:3], v[42:43], 0, s[46:47]
	v_lshlrev_b64 v[32:33], 13, v[2:3]
	v_lshl_or_b32 v32, v109, 4, v32
	s_mov_b64 s[20:21], 0
	v_lshlrev_b32_e32 v126, 4, v109
	v_add_u32_e32 v126, 0x20000, v126
.LBB0_350:
	v_lshl_add_u64 v[120:121], s[94:95], 0, v[32:33]
	v_lshl_add_u64 v[122:123], s[94:95], 0, v[34:35]
	v_add_co_u32_e32 v230, vcc, 0x3a865000, v120
	s_nop 1
	v_addc_co_u32_e32 v231, vcc, 0, v121, vcc
	v_add_co_u32_e32 v222, vcc, 0x3a866000, v120
	s_nop 1
	v_addc_co_u32_e32 v223, vcc, 0, v121, vcc
	v_add_co_u32_e32 v232, vcc, 0x3ac65000, v120
	s_nop 1
	v_addc_co_u32_e32 v233, vcc, 0, v121, vcc
	v_add_co_u32_e32 v224, vcc, 0x3ac66000, v120
	s_nop 1
	v_addc_co_u32_e32 v225, vcc, 0, v121, vcc
	v_add_co_u32_e32 v234, vcc, 0x3b065000, v120
	s_nop 1
	v_addc_co_u32_e32 v235, vcc, 0, v121, vcc
	v_add_co_u32_e32 v226, vcc, 0x3b066000, v120
	s_nop 1
	v_addc_co_u32_e32 v227, vcc, 0, v121, vcc
	v_add_co_u32_e32 v236, vcc, 0x3b465000, v120
	s_nop 1
	v_addc_co_u32_e32 v237, vcc, 0, v121, vcc
	v_add_co_u32_e32 v228, vcc, 0x3b466000, v120
	s_nop 1
	v_addc_co_u32_e32 v229, vcc, 0, v121, vcc
	global_load_dwordx2 v[214:215], v[122:123], off
	global_load_dwordx2 v[216:217], v[122:123], off offset:512
	global_load_dwordx2 v[218:219], v[122:123], off offset:1024
	global_load_dwordx2 v[220:221], v[122:123], off offset:1536
	global_load_dwordx4 v[130:133], v[230:231], off
	global_load_dwordx4 v[134:137], v[230:231], off offset:1024
	global_load_dwordx4 v[138:141], v[230:231], off offset:2048
	global_load_dwordx4 v[142:145], v[230:231], off offset:3072
	global_load_dwordx4 v[146:149], v[232:233], off
	global_load_dwordx4 v[150:153], v[232:233], off offset:1024
	global_load_dwordx4 v[160:163], v[232:233], off offset:2048
	global_load_dwordx4 v[164:167], v[232:233], off offset:3072
	global_load_dwordx4 v[170:173], v[234:235], off
	global_load_dwordx4 v[174:177], v[234:235], off offset:1024
	global_load_dwordx4 v[178:181], v[234:235], off offset:2048
	global_load_dwordx4 v[182:185], v[234:235], off offset:3072
	global_load_dwordx4 v[186:189], v[236:237], off
	global_load_dwordx4 v[190:193], v[236:237], off offset:1024
	global_load_dwordx4 v[194:197], v[236:237], off offset:2048
	global_load_dwordx4 v[210:213], v[236:237], off offset:3072
	s_waitcnt vmcnt(0)
; __device__ __forceinline__ float bf_lo(unsigned w) { return __uint_as_float(w << 16); }
; __device__ __forceinline__ float bf_hi(unsigned w) { return __uint_as_float(w & 0xffff0000u); }
; __device__ __forceinline__ void ln_tail_row(bf16_t* h, const float* part, float scale, const float* g, const float* b, int lane) {
;     ...
;     for (int j = 0; j < 8; ++j) { const int c = 4 * lane + 256 * j; const u32x2 w = *(const u32x2*)(h + c);
;         f32x4 p = *(const f32x4*)(part + c);
; #pragma unroll
;         for (int q = 1; q < 4; ++q) p = p + *(const f32x4*)(part + (size_t)q * 512 * D + c);
;         const f32x4 h4 = {bf_lo(w.x), bf_hi(w.x), bf_lo(w.y), bf_hi(w.y)};
;         v[j] = h4 * ALPHA + p * scale; s += (v[j].x + v[j].y) + (v[j].z + v[j].w); }
	v_lshl_add_u64 v[42:43], s[94:95], 0, v[32:33]
	v_add_co_u32_e32 v44, vcc, 0x3a865000, v42
	v_lshl_add_u64 v[36:37], s[94:95], 0, v[34:35]
	s_nop 0
	v_addc_co_u32_e32 v45, vcc, 0, v43, vcc
	v_add_co_u32_e32 v46, vcc, 0x3ac65000, v42
	v_mov_b32_e32 v38, v214
	v_mov_b32_e32 v39, v215
	v_mov_b32_e32 v2, v130
	v_mov_b32_e32 v3, v131
	v_mov_b32_e32 v4, v132
	v_mov_b32_e32 v5, v133
	v_addc_co_u32_e32 v47, vcc, 0, v43, vcc
	v_mov_b32_e32 v6, v146
	v_mov_b32_e32 v7, v147
	v_mov_b32_e32 v8, v148
	v_mov_b32_e32 v9, v149
	v_add_co_u32_e32 v48, vcc, 0x3b065000, v42
	v_add_u32_e32 v10, s26, v10
	s_nop 0
	v_addc_co_u32_e32 v49, vcc, 0, v43, vcc
	v_add_co_u32_e32 v50, vcc, 0x3b465000, v42
	v_lshl_add_u64 v[32:33], v[32:33], 0, s[4:5]
	s_nop 0
	v_addc_co_u32_e32 v51, vcc, 0, v43, vcc
	v_add_co_u32_e32 v76, vcc, s8, v42
	v_lshl_add_u64 v[34:35], v[34:35], 0, s[6:7]
	s_nop 0
	v_addc_co_u32_e32 v77, vcc, 0, v43, vcc
	v_add_co_u32_e32 v78, vcc, s9, v42
	v_pk_add_f32 v[8:9], v[4:5], v[8:9]
	v_pk_add_f32 v[6:7], v[2:3], v[6:7]
	v_mov_b32_e32 v2, v170
	v_mov_b32_e32 v3, v171
	v_mov_b32_e32 v4, v172
	v_mov_b32_e32 v5, v173
	v_addc_co_u32_e32 v79, vcc, 0, v43, vcc
	v_add_co_u32_e32 v80, vcc, s10, v42
	v_pk_add_f32 v[8:9], v[8:9], v[4:5]
	v_pk_add_f32 v[6:7], v[6:7], v[2:3]
	v_mov_b32_e32 v2, v186
	v_mov_b32_e32 v3, v187
	v_mov_b32_e32 v4, v188
	v_mov_b32_e32 v5, v189
	v_addc_co_u32_e32 v81, vcc, 0, v43, vcc
	v_add_co_u32_e32 v82, vcc, s11, v42
	v_pk_add_f32 v[4:5], v[8:9], v[4:5]
	v_pk_add_f32 v[6:7], v[6:7], v[2:3]
	v_lshlrev_b32_e32 v2, 16, v38
	v_and_b32_e32 v3, 0xffff0000, v38
	v_lshlrev_b32_e32 v8, 16, v39
	v_and_b32_e32 v9, 0xffff0000, v39
	v_pk_mul_f32 v[38:39], v[2:3], s[24:25] op_sel_hi:[1,0]
	v_pk_mul_f32 v[2:3], v[8:9], s[24:25] op_sel_hi:[1,0]
	v_addc_co_u32_e32 v83, vcc, 0, v43, vcc
	v_pk_fma_f32 v[2:3], v[4:5], 0.5, v[2:3] op_sel_hi:[1,0,1]
	v_pk_fma_f32 v[4:5], v[6:7], 0.5, v[38:39] op_sel_hi:[1,0,1]
	v_mov_b32_e32 v52, v216
	v_mov_b32_e32 v53, v217
	v_mov_b32_e32 v6, v134
	v_mov_b32_e32 v7, v135
	v_mov_b32_e32 v8, v136
	v_mov_b32_e32 v9, v137
	v_mov_b32_e32 v38, v150
	v_mov_b32_e32 v39, v151
	v_mov_b32_e32 v40, v152
	v_mov_b32_e32 v41, v153
	v_pk_add_f32 v[40:41], v[8:9], v[40:41]
	v_pk_add_f32 v[38:39], v[6:7], v[38:39]
	v_mov_b32_e32 v6, v174
	v_mov_b32_e32 v7, v175
	v_mov_b32_e32 v8, v176
	v_mov_b32_e32 v9, v177
	v_pk_add_f32 v[40:41], v[40:41], v[8:9]
	v_pk_add_f32 v[38:39], v[38:39], v[6:7]
	v_mov_b32_e32 v6, v190
	v_mov_b32_e32 v7, v191
	v_mov_b32_e32 v8, v192
	v_mov_b32_e32 v9, v193
	v_pk_add_f32 v[6:7], v[38:39], v[6:7]
	v_lshlrev_b32_e32 v38, 16, v52
	v_and_b32_e32 v39, 0xffff0000, v52
	v_pk_add_f32 v[8:9], v[40:41], v[8:9]
	v_lshlrev_b32_e32 v40, 16, v53
	v_and_b32_e32 v41, 0xffff0000, v53
	v_pk_mul_f32 v[38:39], v[38:39], s[24:25] op_sel_hi:[1,0]
	v_pk_mul_f32 v[40:41], v[40:41], s[24:25] op_sel_hi:[1,0]
	v_pk_fma_f32 v[64:65], v[6:7], 0.5, v[38:39] op_sel_hi:[1,0,1]
	v_pk_fma_f32 v[62:63], v[8:9], 0.5, v[40:41] op_sel_hi:[1,0,1]
	v_mov_b32_e32 v6, v4
	v_mov_b32_e32 v7, v64
	v_mov_b32_e32 v8, v5
	v_mov_b32_e32 v9, v65
	v_pk_add_f32 v[6:7], v[6:7], v[8:9]
	v_mov_b32_e32 v8, v2
	v_mov_b32_e32 v9, v62
	v_mov_b32_e32 v38, v3
	v_mov_b32_e32 v39, v63
	v_pk_add_f32 v[8:9], v[8:9], v[38:39]
	s_nop 0
	v_pk_add_f32 v[6:7], v[6:7], v[8:9]
	s_nop 0
	v_add_f32_e32 v6, 0, v6
	v_add_f32_e32 v68, v6, v7
	v_mov_b32_e32 v52, v218
	v_mov_b32_e32 v53, v219
	v_mov_b32_e32 v6, v138
	v_mov_b32_e32 v7, v139
	v_mov_b32_e32 v8, v140
	v_mov_b32_e32 v9, v141
	v_mov_b32_e32 v38, v160
	v_mov_b32_e32 v39, v161
	v_mov_b32_e32 v40, v162
	v_mov_b32_e32 v41, v163
	v_pk_add_f32 v[40:41], v[8:9], v[40:41]
	v_pk_add_f32 v[38:39], v[6:7], v[38:39]
	v_mov_b32_e32 v6, v178
	v_mov_b32_e32 v7, v179
	v_mov_b32_e32 v8, v180
	v_mov_b32_e32 v9, v181
	v_pk_add_f32 v[40:41], v[40:41], v[8:9]
	v_pk_add_f32 v[38:39], v[38:39], v[6:7]
	v_mov_b32_e32 v6, v194
	v_mov_b32_e32 v7, v195
	v_mov_b32_e32 v8, v196
	v_mov_b32_e32 v9, v197
	v_pk_add_f32 v[8:9], v[40:41], v[8:9]
	v_pk_add_f32 v[6:7], v[38:39], v[6:7]
	v_lshlrev_b32_e32 v38, 16, v52
	v_and_b32_e32 v39, 0xffff0000, v52
	v_lshlrev_b32_e32 v40, 16, v53
	v_and_b32_e32 v41, 0xffff0000, v53
	v_pk_mul_f32 v[38:39], v[38:39], s[24:25] op_sel_hi:[1,0]
	v_pk_mul_f32 v[40:41], v[40:41], s[24:25] op_sel_hi:[1,0]
	v_pk_fma_f32 v[60:61], v[6:7], 0.5, v[38:39] op_sel_hi:[1,0,1]
	v_pk_fma_f32 v[58:59], v[8:9], 0.5, v[40:41] op_sel_hi:[1,0,1]
	v_mov_b32_e32 v8, v60
	v_pk_mov_b32 v[6:7], v[60:61], v[58:59] op_sel:[1,0]
	v_mov_b32_e32 v9, v59
	v_pk_add_f32 v[6:7], v[6:7], v[8:9]
	s_nop 0
	v_pk_add_f32 v[70:71], v[6:7], v[6:7] op_sel:[0,1] op_sel_hi:[1,0]
	v_mov_b32_e32 v52, v220
	v_mov_b32_e32 v53, v221
	v_mov_b32_e32 v6, v142
	v_mov_b32_e32 v7, v143
	v_mov_b32_e32 v8, v144
	v_mov_b32_e32 v9, v145
	v_mov_b32_e32 v38, v164
	v_mov_b32_e32 v39, v165
	v_mov_b32_e32 v40, v166
	v_mov_b32_e32 v41, v167
	v_pk_add_f32 v[40:41], v[8:9], v[40:41]
	v_pk_add_f32 v[38:39], v[6:7], v[38:39]
	v_mov_b32_e32 v6, v182
	v_mov_b32_e32 v7, v183
	v_mov_b32_e32 v8, v184
	v_mov_b32_e32 v9, v185
	v_pk_add_f32 v[40:41], v[40:41], v[8:9]
	v_pk_add_f32 v[38:39], v[38:39], v[6:7]
	v_mov_b32_e32 v6, v210
	v_mov_b32_e32 v7, v211
	v_mov_b32_e32 v8, v212
	v_mov_b32_e32 v9, v213
	global_load_dwordx2 v[214:215], v[122:123], off offset:2048
	global_load_dwordx2 v[216:217], v[122:123], off offset:2560
	global_load_dwordx2 v[218:219], v[122:123], off offset:3072
	global_load_dwordx2 v[220:221], v[122:123], off offset:3584
	global_load_dwordx4 v[130:133], v[222:223], off
	global_load_dwordx4 v[134:137], v[222:223], off offset:1024
	global_load_dwordx4 v[138:141], v[222:223], off offset:2048
	global_load_dwordx4 v[142:145], v[222:223], off offset:3072
	global_load_dwordx4 v[146:149], v[224:225], off
	global_load_dwordx4 v[150:153], v[224:225], off offset:1024
	global_load_dwordx4 v[160:163], v[224:225], off offset:2048
	global_load_dwordx4 v[164:167], v[224:225], off offset:3072
	global_load_dwordx4 v[170:173], v[226:227], off
	global_load_dwordx4 v[174:177], v[226:227], off offset:1024
	global_load_dwordx4 v[178:181], v[226:227], off offset:2048
	global_load_dwordx4 v[182:185], v[226:227], off offset:3072
	global_load_dwordx4 v[186:189], v[228:229], off
	global_load_dwordx4 v[190:193], v[228:229], off offset:1024
	global_load_dwordx4 v[194:197], v[228:229], off offset:2048
	global_load_dwordx4 v[210:213], v[228:229], off offset:3072
	s_waitcnt vmcnt(0)
; __device__ __forceinline__ float bf_lo(unsigned w) { return __uint_as_float(w << 16); }
; __device__ __forceinline__ float bf_hi(unsigned w) { return __uint_as_float(w & 0xffff0000u); }
; __device__ __forceinline__ void ln_tail_row(bf16_t* h, const float* part, float scale, const float* g, const float* b, int lane) {
;     ...
;     for (int j = 0; j < 8; ++j) { const int c = 4 * lane + 256 * j; const u32x2 w = *(const u32x2*)(h + c);
;         f32x4 p = *(const f32x4*)(part + c);
; #pragma unroll
;         for (int q = 1; q < 4; ++q) p = p + *(const f32x4*)(part + (size_t)q * 512 * D + c);
;         const f32x4 h4 = {bf_lo(w.x), bf_hi(w.x), bf_lo(w.y), bf_hi(w.y)};
;         v[j] = h4 * ALPHA + p * scale; s += (v[j].x + v[j].y) + (v[j].z + v[j].w); }
;     const float mean = wave_sum(s) * (1.f / D); float s2 = 0.f;
	v_mov_b32_e32 v48, v214
	v_mov_b32_e32 v49, v215
	v_pk_add_f32 v[8:9], v[40:41], v[8:9]
	v_pk_add_f32 v[6:7], v[38:39], v[6:7]
	v_lshlrev_b32_e32 v38, 16, v52
	v_and_b32_e32 v39, 0xffff0000, v52
	v_lshlrev_b32_e32 v40, 16, v53
	v_and_b32_e32 v41, 0xffff0000, v53
	v_pk_mul_f32 v[38:39], v[38:39], s[24:25] op_sel_hi:[1,0]
	v_pk_mul_f32 v[40:41], v[40:41], s[24:25] op_sel_hi:[1,0]
	v_pk_fma_f32 v[56:57], v[6:7], 0.5, v[38:39] op_sel_hi:[1,0,1]
	v_pk_fma_f32 v[54:55], v[8:9], 0.5, v[40:41] op_sel_hi:[1,0,1]
	v_mov_b32_e32 v6, v130
	v_mov_b32_e32 v7, v131
	v_mov_b32_e32 v8, v132
	v_mov_b32_e32 v9, v133
	v_mov_b32_e32 v38, v146
	v_mov_b32_e32 v39, v147
	v_mov_b32_e32 v40, v148
	v_mov_b32_e32 v41, v149
	v_add_f32_e32 v44, v56, v57
	v_add_f32_e32 v46, v54, v55
	v_pk_add_f32 v[40:41], v[8:9], v[40:41]
	v_pk_add_f32 v[38:39], v[6:7], v[38:39]
	v_mov_b32_e32 v6, v170
	v_mov_b32_e32 v7, v171
	v_mov_b32_e32 v8, v172
	v_mov_b32_e32 v9, v173
	v_pk_add_f32 v[40:41], v[40:41], v[8:9]
	v_pk_add_f32 v[38:39], v[38:39], v[6:7]
	v_mov_b32_e32 v6, v186
	v_mov_b32_e32 v7, v187
	v_mov_b32_e32 v8, v188
	v_mov_b32_e32 v9, v189
	v_pk_add_f32 v[8:9], v[40:41], v[8:9]
	v_pk_add_f32 v[6:7], v[38:39], v[6:7]
	v_lshlrev_b32_e32 v38, 16, v48
	v_and_b32_e32 v39, 0xffff0000, v48
	v_lshlrev_b32_e32 v40, 16, v49
	v_and_b32_e32 v41, 0xffff0000, v49
	v_pk_mul_f32 v[38:39], v[38:39], s[24:25] op_sel_hi:[1,0]
	v_pk_mul_f32 v[40:41], v[40:41], s[24:25] op_sel_hi:[1,0]
	v_pk_fma_f32 v[52:53], v[6:7], 0.5, v[38:39] op_sel_hi:[1,0,1]
	v_pk_fma_f32 v[50:51], v[8:9], 0.5, v[40:41] op_sel_hi:[1,0,1]
	v_mov_b32_e32 v69, v52
	v_mov_b32_e32 v71, v53
	v_mov_b32_e32 v45, v50
	v_mov_b32_e32 v47, v51
	v_pk_add_f32 v[6:7], v[68:69], v[70:71]
	v_pk_add_f32 v[8:9], v[44:45], v[46:47]
	s_nop 0
	v_pk_add_f32 v[6:7], v[6:7], v[8:9]
	s_nop 0
	v_pk_add_f32 v[68:69], v[6:7], v[6:7] op_sel:[0,1] op_sel_hi:[1,0]
	v_mov_b32_e32 v42, v216
	v_mov_b32_e32 v43, v217
	v_mov_b32_e32 v6, v134
	v_mov_b32_e32 v7, v135
	v_mov_b32_e32 v8, v136
	v_mov_b32_e32 v9, v137
	v_mov_b32_e32 v38, v150
	v_mov_b32_e32 v39, v151
	v_mov_b32_e32 v40, v152
	v_mov_b32_e32 v41, v153
	v_pk_add_f32 v[40:41], v[8:9], v[40:41]
	v_pk_add_f32 v[38:39], v[6:7], v[38:39]
	v_mov_b32_e32 v6, v174
	v_mov_b32_e32 v7, v175
	v_mov_b32_e32 v8, v176
	v_mov_b32_e32 v9, v177
	v_pk_add_f32 v[40:41], v[40:41], v[8:9]
	v_pk_add_f32 v[38:39], v[38:39], v[6:7]
	v_mov_b32_e32 v6, v190
	v_mov_b32_e32 v7, v191
	v_mov_b32_e32 v8, v192
	v_mov_b32_e32 v9, v193
	v_pk_add_f32 v[8:9], v[40:41], v[8:9]
	v_pk_add_f32 v[6:7], v[38:39], v[6:7]
	v_lshlrev_b32_e32 v38, 16, v42
	v_and_b32_e32 v39, 0xffff0000, v42
	v_lshlrev_b32_e32 v40, 16, v43
	v_and_b32_e32 v41, 0xffff0000, v43
	v_pk_mul_f32 v[38:39], v[38:39], s[24:25] op_sel_hi:[1,0]
	v_pk_mul_f32 v[40:41], v[40:41], s[24:25] op_sel_hi:[1,0]
	v_pk_fma_f32 v[48:49], v[6:7], 0.5, v[38:39] op_sel_hi:[1,0,1]
	v_pk_fma_f32 v[46:47], v[8:9], 0.5, v[40:41] op_sel_hi:[1,0,1]
	v_mov_b32_e32 v8, v48
	v_pk_mov_b32 v[6:7], v[48:49], v[46:47] op_sel:[1,0]
	v_mov_b32_e32 v9, v47
	v_pk_add_f32 v[6:7], v[6:7], v[8:9]
	s_nop 0
	v_pk_add_f32 v[70:71], v[6:7], v[6:7] op_sel:[0,1] op_sel_hi:[1,0]
	v_mov_b32_e32 v42, v218
	v_mov_b32_e32 v43, v219
	v_mov_b32_e32 v6, v138
	v_mov_b32_e32 v7, v139
	v_mov_b32_e32 v8, v140
	v_mov_b32_e32 v9, v141
	v_mov_b32_e32 v38, v160
	v_mov_b32_e32 v39, v161
	v_mov_b32_e32 v40, v162
	v_mov_b32_e32 v41, v163
	v_pk_add_f32 v[40:41], v[8:9], v[40:41]
	v_pk_add_f32 v[38:39], v[6:7], v[38:39]
	v_mov_b32_e32 v6, v178
	v_mov_b32_e32 v7, v179
	v_mov_b32_e32 v8, v180
	v_mov_b32_e32 v9, v181
	v_pk_add_f32 v[40:41], v[40:41], v[8:9]
	v_pk_add_f32 v[38:39], v[38:39], v[6:7]
	v_mov_b32_e32 v6, v194
	v_mov_b32_e32 v7, v195
	v_mov_b32_e32 v8, v196
	v_mov_b32_e32 v9, v197
	v_pk_add_f32 v[8:9], v[40:41], v[8:9]
	v_pk_add_f32 v[6:7], v[38:39], v[6:7]
	v_lshlrev_b32_e32 v38, 16, v42
	v_and_b32_e32 v39, 0xffff0000, v42
	v_lshlrev_b32_e32 v40, 16, v43
	v_and_b32_e32 v41, 0xffff0000, v43
	v_pk_mul_f32 v[38:39], v[38:39], s[24:25] op_sel_hi:[1,0]
	v_pk_mul_f32 v[40:41], v[40:41], s[24:25] op_sel_hi:[1,0]
	v_pk_fma_f32 v[44:45], v[6:7], 0.5, v[38:39] op_sel_hi:[1,0,1]
	v_pk_fma_f32 v[42:43], v[8:9], 0.5, v[40:41] op_sel_hi:[1,0,1]
	v_mov_b32_e32 v88, v220
	v_mov_b32_e32 v89, v221
	v_mov_b32_e32 v6, v142
	v_mov_b32_e32 v7, v143
	v_mov_b32_e32 v8, v144
	v_mov_b32_e32 v9, v145
	v_mov_b32_e32 v38, v164
	v_mov_b32_e32 v39, v165
	v_mov_b32_e32 v40, v166
	v_mov_b32_e32 v41, v167
	v_add_f32_e32 v84, v44, v45
	v_add_f32_e32 v86, v42, v43
	v_pk_add_f32 v[40:41], v[8:9], v[40:41]
	v_pk_add_f32 v[38:39], v[6:7], v[38:39]
	v_mov_b32_e32 v6, v182
	v_mov_b32_e32 v7, v183
	v_mov_b32_e32 v8, v184
	v_mov_b32_e32 v9, v185
	v_pk_add_f32 v[40:41], v[40:41], v[8:9]
	v_pk_add_f32 v[38:39], v[38:39], v[6:7]
	v_mov_b32_e32 v6, v210
	v_mov_b32_e32 v7, v211
	v_mov_b32_e32 v8, v212
	v_mov_b32_e32 v9, v213
	v_pk_add_f32 v[8:9], v[40:41], v[8:9]
	v_pk_add_f32 v[6:7], v[38:39], v[6:7]
	v_lshlrev_b32_e32 v38, 16, v88
	v_and_b32_e32 v39, 0xffff0000, v88
	v_lshlrev_b32_e32 v40, 16, v89
	v_and_b32_e32 v41, 0xffff0000, v89
	v_pk_mul_f32 v[76:77], v[38:39], s[24:25] op_sel_hi:[1,0]
	v_pk_mul_f32 v[38:39], v[40:41], s[24:25] op_sel_hi:[1,0]
	v_pk_fma_f32 v[40:41], v[6:7], 0.5, v[76:77] op_sel_hi:[1,0,1]
	v_pk_fma_f32 v[38:39], v[8:9], 0.5, v[38:39] op_sel_hi:[1,0,1]
	v_mov_b32_e32 v69, v40
	v_mov_b32_e32 v71, v41
	v_mov_b32_e32 v85, v38
	v_mov_b32_e32 v87, v39
	v_pk_add_f32 v[6:7], v[68:69], v[70:71]
	v_pk_add_f32 v[8:9], v[84:85], v[86:87]
	s_nop 0
	v_pk_add_f32 v[6:7], v[6:7], v[8:9]
	s_nop 0
	v_add_f32_e32 v6, v6, v7
	ds_bpermute_b32 v7, v1, v6
	s_waitcnt lgkmcnt(0)
; __device__ __forceinline__ void ln_tail_row(bf16_t* h, const float* part, float scale, const float* g, const float* b, int lane) {
;     ...
;     const float mean = wave_sum(s) * (1.f / D); float s2 = 0.f;
; #pragma unroll
;     for (int j = 0; j < 8; ++j) { v[j] = v[j] - mean; s2 += (v[j].x * v[j].x + v[j].y * v[j].y) + (v[j].z * v[j].z + v[j].w * v[j].w); }
;     const float rstd = rsqrtf(wave_sum(s2) * (1.f / D) + LN_EPS);
	v_add_f32_e32 v6, v6, v7
	ds_bpermute_b32 v7, v67, v6
	s_waitcnt lgkmcnt(0)
	v_add_f32_e32 v6, v6, v7
	ds_bpermute_b32 v7, v72, v6
	s_waitcnt lgkmcnt(0)
	v_add_f32_e32 v6, v6, v7
	ds_bpermute_b32 v7, v73, v6
	s_waitcnt lgkmcnt(0)
	v_add_f32_e32 v6, v6, v7
	ds_bpermute_b32 v7, v74, v6
	s_waitcnt lgkmcnt(0)
	v_add_f32_e32 v6, v6, v7
	ds_bpermute_b32 v7, v75, v6
	s_waitcnt lgkmcnt(0)
	v_add_f32_e32 v11, v6, v7
	v_fmamk_f32 v5, v11, 0xba000000, v5
	v_fmamk_f32 v65, v11, 0xba000000, v65
	v_fmamk_f32 v3, v11, 0xba000000, v3
	v_fmac_f32_e32 v4, 0xba000000, v11
	v_fmamk_f32 v63, v11, 0xba000000, v63
	v_fmac_f32_e32 v64, 0xba000000, v11
	v_mov_b32_e32 v8, v5
	v_mov_b32_e32 v9, v65
	v_fmac_f32_e32 v2, 0xba000000, v11
	v_fmac_f32_e32 v62, 0xba000000, v11
	v_mov_b32_e32 v6, v4
	v_mov_b32_e32 v7, v64
	v_pk_mul_f32 v[8:9], v[8:9], v[8:9]
	v_mov_b32_e32 v68, v3
	v_mov_b32_e32 v69, v63
	v_pk_fma_f32 v[6:7], v[6:7], v[6:7], v[8:9]
	v_mov_b32_e32 v8, v2
	v_mov_b32_e32 v9, v62
	v_pk_mul_f32 v[68:69], v[68:69], v[68:69]
	v_fmamk_f32 v61, v11, 0xba000000, v61
	v_pk_fma_f32 v[8:9], v[8:9], v[8:9], v[68:69]
	v_fmac_f32_e32 v60, 0xba000000, v11
	v_pk_add_f32 v[6:7], v[6:7], v[8:9]
	v_fmamk_f32 v59, v11, 0xba000000, v59
	v_fmac_f32_e32 v58, 0xba000000, v11
	v_pk_add_f32 v[6:7], v[6:7], v[6:7] op_sel_hi:[0,1]
	v_pk_mul_f32 v[8:9], v[58:59], v[58:59]
	v_pk_mul_f32 v[68:69], v[60:61], v[60:61]
	v_fmac_f32_e32 v56, 0xba000000, v11
	v_pk_mov_b32 v[70:71], v[68:69], v[8:9] op_sel:[1,0]
	v_mov_b32_e32 v69, v9
	v_fmamk_f32 v57, v11, 0xba000000, v57
	v_fmac_f32_e32 v54, 0xba000000, v11
	v_mul_f32_e32 v6, v56, v56
	v_pk_add_f32 v[8:9], v[70:71], v[68:69]
	v_fmamk_f32 v55, v11, 0xba000000, v55
	v_pk_fma_f32 v[68:69], v[56:57], v[56:57], v[6:7] op_sel_hi:[1,1,0]
	v_mul_f32_e32 v6, v54, v54
	v_pk_add_f32 v[8:9], v[8:9], v[8:9] op_sel_hi:[0,1]
	v_pk_fma_f32 v[70:71], v[54:55], v[54:55], v[6:7] op_sel_hi:[1,1,0]
	v_fmamk_f32 v51, v11, 0xba000000, v51
	v_fmac_f32_e32 v50, 0xba000000, v11
	v_fmamk_f32 v53, v11, 0xba000000, v53
	v_fmac_f32_e32 v52, 0xba000000, v11
	v_mul_f32_e32 v68, v52, v52
	v_mul_f32_e32 v70, v53, v53
	v_mul_f32_e32 v8, v50, v50
	v_mul_f32_e32 v6, v51, v51
	v_pk_add_f32 v[68:69], v[68:69], v[70:71]
	v_pk_add_f32 v[6:7], v[8:9], v[6:7]
	v_fmamk_f32 v49, v11, 0xba000000, v49
	v_pk_add_f32 v[6:7], v[68:69], v[6:7]
	v_fmac_f32_e32 v48, 0xba000000, v11
	v_fmamk_f32 v47, v11, 0xba000000, v47
	v_fmac_f32_e32 v46, 0xba000000, v11
	v_pk_add_f32 v[6:7], v[6:7], v[6:7] op_sel_hi:[0,1]
	v_pk_mul_f32 v[8:9], v[46:47], v[46:47]
	v_pk_mul_f32 v[68:69], v[48:49], v[48:49]
	v_fmac_f32_e32 v44, 0xba000000, v11
	v_pk_mov_b32 v[70:71], v[68:69], v[8:9] op_sel:[1,0]
	v_mov_b32_e32 v69, v9
	v_fmamk_f32 v45, v11, 0xba000000, v45
	v_fmac_f32_e32 v42, 0xba000000, v11
	v_mul_f32_e32 v6, v44, v44
	v_pk_add_f32 v[8:9], v[70:71], v[68:69]
	v_fmamk_f32 v43, v11, 0xba000000, v43
	v_pk_fma_f32 v[68:69], v[44:45], v[44:45], v[6:7] op_sel_hi:[1,1,0]
	v_mul_f32_e32 v6, v42, v42
	v_pk_add_f32 v[8:9], v[8:9], v[8:9] op_sel_hi:[0,1]
	v_pk_fma_f32 v[70:71], v[42:43], v[42:43], v[6:7] op_sel_hi:[1,1,0]
	v_fmamk_f32 v39, v11, 0xba000000, v39
	v_fmac_f32_e32 v38, 0xba000000, v11
	v_fmamk_f32 v41, v11, 0xba000000, v41
	v_fmac_f32_e32 v40, 0xba000000, v11
	v_mul_f32_e32 v68, v40, v40
	v_mul_f32_e32 v70, v41, v41
	v_mul_f32_e32 v8, v38, v38
	v_mul_f32_e32 v6, v39, v39
	v_pk_add_f32 v[68:69], v[68:69], v[70:71]
	v_pk_add_f32 v[6:7], v[8:9], v[6:7]
	s_nop 0
	v_pk_add_f32 v[6:7], v[68:69], v[6:7]
	s_nop 0
	v_add_f32_e32 v6, v6, v7
	ds_bpermute_b32 v7, v1, v6
	s_waitcnt lgkmcnt(0)
	v_add_f32_e32 v6, v6, v7
	ds_bpermute_b32 v7, v67, v6
	s_waitcnt lgkmcnt(0)
	v_add_f32_e32 v6, v6, v7
	ds_bpermute_b32 v7, v72, v6
	s_waitcnt lgkmcnt(0)
	v_add_f32_e32 v6, v6, v7
	ds_bpermute_b32 v7, v73, v6
	s_waitcnt lgkmcnt(0)
	v_add_f32_e32 v6, v6, v7
	ds_bpermute_b32 v7, v74, v6
	s_waitcnt lgkmcnt(0)
	v_add_f32_e32 v6, v6, v7
	ds_bpermute_b32 v7, v75, v6
	s_waitcnt lgkmcnt(0)
; __device__ __forceinline__ unsigned cvt_pk_bf16(float lo, float hi) { unsigned r; asm volatile("v_cvt_pk_bf16_f32 %0, %1, %2" : "=v"(r) : "v"(lo), "v"(hi)); return r; }
; __device__ __forceinline__ void ln_tail_row(bf16_t* h, const float* part, float scale, const float* g, const float* b, int lane) {
;     ...
;     const float rstd = rsqrtf(wave_sum(s2) * (1.f / D) + LN_EPS);
; #pragma unroll
;     for (int j = 0; j < 8; ++j) { const int c = 4 * lane + 256 * j; const f32x4 y = v[j] * rstd * *(const f32x4*)(g + c) + *(const f32x4*)(b + c);
;         u32x2 w; w.x = cvt_pk_bf16(y.x, y.y); w.y = cvt_pk_bf16(y.z, y.w); *(u32x2*)(h + c) = w; }
	v_add_f32_e32 v6, v6, v7
	v_fmamk_f32 v6, v6, 0x3a000000, v154
	v_cmp_gt_f32_e32 vcc, s73, v6
	v_mul_f32_e32 v7, 0x4b800000, v6
	s_nop 0
	v_cndmask_b32_e32 v6, v6, v7, vcc
	v_rsq_f32_e32 v6, v6
	s_nop 0
	v_mul_f32_e32 v7, 0x45800000, v6
	v_cndmask_b32_e32 v66, v6, v7, vcc
	v_pk_mul_f32 v[68:69], v[4:5], v[66:67] op_sel_hi:[1,0]
	v_pk_mul_f32 v[70:71], v[2:3], v[66:67] op_sel_hi:[1,0]
	ds_read_b128 v[2:5], v126
	ds_read_b128 v[6:9], v126 offset:8192
	v_pk_mul_f32 v[64:65], v[64:65], v[66:67] op_sel_hi:[1,0]
	v_pk_mul_f32 v[62:63], v[62:63], v[66:67] op_sel_hi:[1,0]
	v_pk_mul_f32 v[60:61], v[60:61], v[66:67] op_sel_hi:[1,0]
	v_pk_mul_f32 v[58:59], v[58:59], v[66:67] op_sel_hi:[1,0]
	v_pk_mul_f32 v[56:57], v[56:57], v[66:67] op_sel_hi:[1,0]
	v_pk_mul_f32 v[54:55], v[54:55], v[66:67] op_sel_hi:[1,0]
	v_pk_mul_f32 v[52:53], v[52:53], v[66:67] op_sel_hi:[1,0]
	v_pk_mul_f32 v[50:51], v[50:51], v[66:67] op_sel_hi:[1,0]
	v_pk_mul_f32 v[48:49], v[48:49], v[66:67] op_sel_hi:[1,0]
	v_pk_mul_f32 v[46:47], v[46:47], v[66:67] op_sel_hi:[1,0]
	v_pk_mul_f32 v[44:45], v[44:45], v[66:67] op_sel_hi:[1,0]
	v_pk_mul_f32 v[42:43], v[42:43], v[66:67] op_sel_hi:[1,0]
	v_pk_mul_f32 v[40:41], v[40:41], v[66:67] op_sel_hi:[1,0]
	v_cmp_lt_i32_e32 vcc, s12, v10
	v_pk_mul_f32 v[38:39], v[38:39], v[66:67] op_sel_hi:[1,0]
	s_or_b64 s[20:21], vcc, s[20:21]
	s_waitcnt lgkmcnt(0)
	v_pk_fma_f32 v[2:3], v[2:3], v[68:69], v[6:7]
	v_pk_fma_f32 v[4:5], v[4:5], v[70:71], v[8:9]
	v_cvt_pk_bf16_f32 v2, v2, v3
	s_nop 0
	v_cvt_pk_bf16_f32 v3, v4, v5
	global_store_dwordx2 v[36:37], v[2:3], off
	s_nop 1
	ds_read_b128 v[2:5], v126 offset:1024
	s_nop 0
	ds_read_b128 v[6:9], v126 offset:9216
	s_waitcnt lgkmcnt(0)
	v_pk_fma_f32 v[2:3], v[2:3], v[64:65], v[6:7]
	v_pk_fma_f32 v[4:5], v[4:5], v[62:63], v[8:9]
	v_cvt_pk_bf16_f32 v2, v2, v3
	s_nop 0
	v_cvt_pk_bf16_f32 v3, v4, v5
	global_store_dwordx2 v[36:37], v[2:3], off offset:512
	s_nop 1
	ds_read_b128 v[2:5], v126 offset:2048
	s_nop 0
	ds_read_b128 v[6:9], v126 offset:10240
	s_waitcnt lgkmcnt(0)
	v_pk_fma_f32 v[2:3], v[2:3], v[60:61], v[6:7]
	v_pk_fma_f32 v[4:5], v[4:5], v[58:59], v[8:9]
	v_cvt_pk_bf16_f32 v2, v2, v3
	s_nop 0
	v_cvt_pk_bf16_f32 v3, v4, v5
	global_store_dwordx2 v[36:37], v[2:3], off offset:1024
	s_nop 1
	ds_read_b128 v[2:5], v126 offset:3072
	s_nop 0
	ds_read_b128 v[6:9], v126 offset:11264
	s_waitcnt lgkmcnt(0)
	v_pk_fma_f32 v[2:3], v[2:3], v[56:57], v[6:7]
	v_pk_fma_f32 v[4:5], v[4:5], v[54:55], v[8:9]
	v_cvt_pk_bf16_f32 v2, v2, v3
	s_nop 0
	v_cvt_pk_bf16_f32 v3, v4, v5
	global_store_dwordx2 v[36:37], v[2:3], off offset:1536
	s_nop 1
	ds_read_b128 v[2:5], v126 offset:4096
	s_nop 0
	ds_read_b128 v[6:9], v126 offset:12288
	s_waitcnt lgkmcnt(0)
	v_pk_fma_f32 v[2:3], v[2:3], v[52:53], v[6:7]
	v_pk_fma_f32 v[4:5], v[4:5], v[50:51], v[8:9]
	v_cvt_pk_bf16_f32 v2, v2, v3
	s_nop 0
	v_cvt_pk_bf16_f32 v3, v4, v5
	global_store_dwordx2 v[36:37], v[2:3], off offset:2048
	s_nop 1
	ds_read_b128 v[2:5], v126 offset:5120
	s_nop 0
	ds_read_b128 v[6:9], v126 offset:13312
	s_waitcnt lgkmcnt(0)
	v_pk_fma_f32 v[2:3], v[2:3], v[48:49], v[6:7]
	v_pk_fma_f32 v[4:5], v[4:5], v[46:47], v[8:9]
	v_cvt_pk_bf16_f32 v2, v2, v3
	s_nop 0
	v_cvt_pk_bf16_f32 v3, v4, v5
	global_store_dwordx2 v[36:37], v[2:3], off offset:2560
	s_nop 1
	ds_read_b128 v[2:5], v126 offset:6144
	s_nop 0
	ds_read_b128 v[6:9], v126 offset:14336
	s_waitcnt lgkmcnt(0)
	v_pk_fma_f32 v[2:3], v[2:3], v[44:45], v[6:7]
	v_pk_fma_f32 v[4:5], v[4:5], v[42:43], v[8:9]
	v_cvt_pk_bf16_f32 v2, v2, v3
	s_nop 0
	v_cvt_pk_bf16_f32 v3, v4, v5
	global_store_dwordx2 v[36:37], v[2:3], off offset:3072
	s_nop 1
	ds_read_b128 v[2:5], v126 offset:7168
	s_nop 0
	ds_read_b128 v[6:9], v126 offset:15360
	s_waitcnt lgkmcnt(0)
	v_pk_fma_f32 v[2:3], v[40:41], v[2:3], v[6:7]
	v_pk_fma_f32 v[4:5], v[38:39], v[4:5], v[8:9]
	v_cvt_pk_bf16_f32 v2, v2, v3
	s_nop 0
	v_cvt_pk_bf16_f32 v3, v4, v5
	global_store_dwordx2 v[36:37], v[2:3], off offset:3584
	s_andn2_b64 exec, exec, s[20:21]
	s_cbranch_execnz .LBB0_350

; __device__ __forceinline__ float bf_lo(unsigned w) { return __uint_as_float(w << 16); }
; __device__ __forceinline__ float bf_hi(unsigned w) { return __uint_as_float(w & 0xffff0000u); }
; __device__ __forceinline__ void ln_tail_row(bf16_t* h, const float* part, float scale, const float* g, const float* b, int lane) {
;     f32x4 v[8]; float s = 0.f;
; #pragma unroll
;     for (int j = 0; j < 8; ++j) { const int c = 4 * lane + 256 * j; const u32x2 w = *(const u32x2*)(h + c);
;         f32x4 p = *(const f32x4*)(part + c);
; #pragma unroll
;         for (int q = 1; q < 4; ++q) p = p + *(const f32x4*)(part + (size_t)q * 512 * D + c);
;         const f32x4 h4 = {bf_lo(w.x), bf_hi(w.x), bf_lo(w.y), bf_hi(w.y)};
;         v[j] = h4 * ALPHA + p * scale; s += (v[j].x + v[j].y) + (v[j].z + v[j].w); }
; template <int MODE>
; __device__ __forceinline__ void ln_phase(const Args& a, const float* g, const float* b, int nrows, float scale) {
;     ...
;         for (int r = NTOK + gw; r < nrows; r += NGW) ln_tail_row(hb + (size_t)r * D, (const float*)(a.ws + WS_PART) + (size_t)(r - NTOK) * D, scale, g, b, lane);
.LBB0_426:
	s_or_b64 exec, exec, s[42:43]
	s_movk_i32 s0, 0x200
	v_cmp_gt_i32_e32 vcc, s0, v43
	s_and_saveexec_b64 s[2:3], vcc
	v_readlane_b32 s4, v253, 49
	v_readlane_b32 s6, v253, 51
	v_readlane_b32 s40, v253, 58
	v_readlane_b32 s5, v253, 50
	v_readlane_b32 s7, v253, 52
	s_mov_b32 s8, 0x3a866000
	s_mov_b32 s9, 0x3ac66000
	s_mov_b32 s10, 0x3b066000
	s_mov_b32 s11, 0x3b466000
	s_mov_b32 s16, 0xc1ff
	v_readlane_b32 s46, v254, 0
	v_readlane_b32 s47, v254, 1
	v_readlane_b32 s41, v253, 59
	v_readlane_b32 s42, v253, 60
	v_readlane_b32 s43, v253, 61
	v_readlane_b32 s44, v253, 62
	v_readlane_b32 s45, v253, 63
	s_cbranch_execz .LBB0_429
	v_xor_b32_e32 v1, 1, v201
	v_cmp_lt_i32_e32 vcc, v1, v202
	v_xor_b32_e32 v2, 2, v201
	v_mov_b32_e32 v3, v0
	v_cndmask_b32_e32 v1, v201, v1, vcc
	v_cmp_lt_i32_e32 vcc, v2, v202
	v_add_u32_e32 v10, 0xc000, v43
	v_ashrrev_i32_e32 v43, 31, v42
	v_cndmask_b32_e32 v2, v201, v2, vcc
	s_waitcnt vmcnt(0)
	v_lshlrev_b32_e32 v67, 2, v2
	v_xor_b32_e32 v2, 4, v201
	v_cmp_lt_i32_e32 vcc, v2, v202
	s_ashr_i32 s37, s36, 31
	v_ashrrev_i32_e32 v11, 31, v10
	v_cndmask_b32_e32 v2, v201, v2, vcc
	v_lshlrev_b32_e32 v72, 2, v2
	v_xor_b32_e32 v2, 8, v201
	v_cmp_lt_i32_e32 vcc, v2, v202
	v_mov_b32_e32 v45, v0
	v_lshlrev_b64 v[34:35], 12, v[10:11]
	v_cndmask_b32_e32 v2, v201, v2, vcc
	v_lshlrev_b32_e32 v73, 2, v2
	v_xor_b32_e32 v2, 16, v201
	v_cmp_lt_i32_e32 vcc, v2, v202
	v_lshlrev_b32_e32 v1, 2, v1
	v_lshl_add_u64 v[12:13], s[12:13], 0, v[44:45]
	v_cndmask_b32_e32 v2, v201, v2, vcc
	v_lshlrev_b32_e32 v74, 2, v2
	v_xor_b32_e32 v2, 32, v201
	v_cmp_lt_i32_e32 vcc, v2, v202
	v_lshl_add_u64 v[14:15], s[30:31], 0, v[44:45]
	v_lshl_or_b32 v34, v109, 3, v34
	v_cndmask_b32_e32 v2, v201, v2, vcc
	v_lshlrev_b32_e32 v75, 2, v2
	v_or_b32_e32 v2, 0x1000, v44
	v_lshl_add_u64 v[16:17], s[12:13], 0, v[2:3]
	v_lshl_add_u64 v[18:19], s[30:31], 0, v[2:3]
	v_or_b32_e32 v2, 0x1400, v44
	v_lshl_add_u64 v[20:21], s[12:13], 0, v[2:3]
	v_lshl_add_u64 v[22:23], s[30:31], 0, v[2:3]
	v_or_b32_e32 v2, 0x1800, v44
	v_lshl_add_u64 v[24:25], s[12:13], 0, v[2:3]
	v_lshl_add_u64 v[26:27], s[30:31], 0, v[2:3]
	v_or_b32_e32 v2, 0x1c00, v44
	v_lshl_add_u64 v[28:29], s[12:13], 0, v[2:3]
	v_lshl_add_u64 v[30:31], s[30:31], 0, v[2:3]
	v_lshl_add_u64 v[2:3], v[42:43], 0, s[36:37]
	v_lshlrev_b64 v[32:33], 13, v[2:3]
	v_lshl_or_b32 v32, v109, 4, v32
	s_mov_b64 s[12:13], 0
	v_lshlrev_b32_e32 v126, 4, v109
	v_add_u32_e32 v126, 0x20000, v126
.LBB0_428:
	v_lshl_add_u64 v[120:121], s[46:47], 0, v[32:33]
	v_lshl_add_u64 v[122:123], s[46:47], 0, v[34:35]
	v_add_co_u32_e32 v230, vcc, 0x3a865000, v120
	s_nop 1
	v_addc_co_u32_e32 v231, vcc, 0, v121, vcc
	v_add_co_u32_e32 v222, vcc, 0x3a866000, v120
	s_nop 1
	v_addc_co_u32_e32 v223, vcc, 0, v121, vcc
	v_add_co_u32_e32 v232, vcc, 0x3ac65000, v120
	s_nop 1
	v_addc_co_u32_e32 v233, vcc, 0, v121, vcc
	v_add_co_u32_e32 v224, vcc, 0x3ac66000, v120
	s_nop 1
	v_addc_co_u32_e32 v225, vcc, 0, v121, vcc
	v_add_co_u32_e32 v234, vcc, 0x3b065000, v120
	s_nop 1
	v_addc_co_u32_e32 v235, vcc, 0, v121, vcc
	v_add_co_u32_e32 v226, vcc, 0x3b066000, v120
	s_nop 1
	v_addc_co_u32_e32 v227, vcc, 0, v121, vcc
	v_add_co_u32_e32 v236, vcc, 0x3b465000, v120
	s_nop 1
	v_addc_co_u32_e32 v237, vcc, 0, v121, vcc
	v_add_co_u32_e32 v228, vcc, 0x3b466000, v120
	s_nop 1
	v_addc_co_u32_e32 v229, vcc, 0, v121, vcc
	global_load_dwordx2 v[214:215], v[122:123], off
	global_load_dwordx2 v[216:217], v[122:123], off offset:512
	global_load_dwordx2 v[218:219], v[122:123], off offset:1024
	global_load_dwordx2 v[220:221], v[122:123], off offset:1536
	global_load_dwordx4 v[130:133], v[230:231], off
	global_load_dwordx4 v[134:137], v[230:231], off offset:1024
	global_load_dwordx4 v[138:141], v[230:231], off offset:2048
	global_load_dwordx4 v[142:145], v[230:231], off offset:3072
	global_load_dwordx4 v[146:149], v[232:233], off
	global_load_dwordx4 v[150:153], v[232:233], off offset:1024
	global_load_dwordx4 v[160:163], v[232:233], off offset:2048
	global_load_dwordx4 v[164:167], v[232:233], off offset:3072
	global_load_dwordx4 v[170:173], v[234:235], off
	global_load_dwordx4 v[174:177], v[234:235], off offset:1024
	global_load_dwordx4 v[178:181], v[234:235], off offset:2048
	global_load_dwordx4 v[182:185], v[234:235], off offset:3072
	global_load_dwordx4 v[186:189], v[236:237], off
	global_load_dwordx4 v[190:193], v[236:237], off offset:1024
	global_load_dwordx4 v[194:197], v[236:237], off offset:2048
	global_load_dwordx4 v[210:213], v[236:237], off offset:3072
	s_waitcnt vmcnt(0)
; __device__ __forceinline__ float bf_lo(unsigned w) { return __uint_as_float(w << 16); }
; __device__ __forceinline__ float bf_hi(unsigned w) { return __uint_as_float(w & 0xffff0000u); }
; __device__ __forceinline__ void ln_tail_row(bf16_t* h, const float* part, float scale, const float* g, const float* b, int lane) {
;     ...
;     for (int j = 0; j < 8; ++j) { const int c = 4 * lane + 256 * j; const u32x2 w = *(const u32x2*)(h + c);
;         f32x4 p = *(const f32x4*)(part + c);
; #pragma unroll
;         for (int q = 1; q < 4; ++q) p = p + *(const f32x4*)(part + (size_t)q * 512 * D + c);
;         const f32x4 h4 = {bf_lo(w.x), bf_hi(w.x), bf_lo(w.y), bf_hi(w.y)};
;         v[j] = h4 * ALPHA + p * scale; s += (v[j].x + v[j].y) + (v[j].z + v[j].w); }
	v_lshl_add_u64 v[42:43], s[46:47], 0, v[32:33]
	v_add_co_u32_e32 v44, vcc, 0x3a865000, v42
	v_lshl_add_u64 v[36:37], s[46:47], 0, v[34:35]
	s_nop 0
	v_addc_co_u32_e32 v45, vcc, 0, v43, vcc
	v_add_co_u32_e32 v46, vcc, 0x3ac65000, v42
	v_mov_b32_e32 v38, v214
	v_mov_b32_e32 v39, v215
	v_mov_b32_e32 v2, v130
	v_mov_b32_e32 v3, v131
	v_mov_b32_e32 v4, v132
	v_mov_b32_e32 v5, v133
	v_addc_co_u32_e32 v47, vcc, 0, v43, vcc
	v_mov_b32_e32 v6, v146
	v_mov_b32_e32 v7, v147
	v_mov_b32_e32 v8, v148
	v_mov_b32_e32 v9, v149
	v_add_co_u32_e32 v48, vcc, 0x3b065000, v42
	v_add_u32_e32 v10, s26, v10
	s_nop 0
	v_addc_co_u32_e32 v49, vcc, 0, v43, vcc
	v_add_co_u32_e32 v50, vcc, 0x3b465000, v42
	v_lshl_add_u64 v[32:33], v[32:33], 0, s[4:5]
	s_nop 0
	v_addc_co_u32_e32 v51, vcc, 0, v43, vcc
	v_add_co_u32_e32 v76, vcc, s8, v42
	v_lshl_add_u64 v[34:35], v[34:35], 0, s[6:7]
	s_nop 0
	v_addc_co_u32_e32 v77, vcc, 0, v43, vcc
	v_add_co_u32_e32 v78, vcc, s9, v42
	v_pk_add_f32 v[8:9], v[4:5], v[8:9]
	v_pk_add_f32 v[6:7], v[2:3], v[6:7]
	v_mov_b32_e32 v2, v170
	v_mov_b32_e32 v3, v171
	v_mov_b32_e32 v4, v172
	v_mov_b32_e32 v5, v173
	v_addc_co_u32_e32 v79, vcc, 0, v43, vcc
	v_add_co_u32_e32 v80, vcc, s10, v42
	v_pk_add_f32 v[8:9], v[8:9], v[4:5]
	v_pk_add_f32 v[6:7], v[6:7], v[2:3]
	v_mov_b32_e32 v2, v186
	v_mov_b32_e32 v3, v187
	v_mov_b32_e32 v4, v188
	v_mov_b32_e32 v5, v189
	v_addc_co_u32_e32 v81, vcc, 0, v43, vcc
	v_add_co_u32_e32 v82, vcc, s11, v42
	v_pk_add_f32 v[4:5], v[8:9], v[4:5]
	v_pk_add_f32 v[6:7], v[6:7], v[2:3]
	v_lshlrev_b32_e32 v2, 16, v38
	v_and_b32_e32 v3, 0xffff0000, v38
	v_lshlrev_b32_e32 v8, 16, v39
	v_and_b32_e32 v9, 0xffff0000, v39
	v_pk_mul_f32 v[38:39], v[2:3], s[24:25] op_sel_hi:[1,0]
	v_pk_mul_f32 v[2:3], v[8:9], s[24:25] op_sel_hi:[1,0]
	v_addc_co_u32_e32 v83, vcc, 0, v43, vcc
	v_pk_fma_f32 v[2:3], v[4:5], 0.5, v[2:3] op_sel_hi:[1,0,1]
	v_pk_fma_f32 v[4:5], v[6:7], 0.5, v[38:39] op_sel_hi:[1,0,1]
	v_mov_b32_e32 v52, v216
	v_mov_b32_e32 v53, v217
	v_mov_b32_e32 v6, v134
	v_mov_b32_e32 v7, v135
	v_mov_b32_e32 v8, v136
	v_mov_b32_e32 v9, v137
	v_mov_b32_e32 v38, v150
	v_mov_b32_e32 v39, v151
	v_mov_b32_e32 v40, v152
	v_mov_b32_e32 v41, v153
	v_pk_add_f32 v[40:41], v[8:9], v[40:41]
	v_pk_add_f32 v[38:39], v[6:7], v[38:39]
	v_mov_b32_e32 v6, v174
	v_mov_b32_e32 v7, v175
	v_mov_b32_e32 v8, v176
	v_mov_b32_e32 v9, v177
	v_pk_add_f32 v[40:41], v[40:41], v[8:9]
	v_pk_add_f32 v[38:39], v[38:39], v[6:7]
	v_mov_b32_e32 v6, v190
	v_mov_b32_e32 v7, v191
	v_mov_b32_e32 v8, v192
	v_mov_b32_e32 v9, v193
	v_pk_add_f32 v[6:7], v[38:39], v[6:7]
	v_lshlrev_b32_e32 v38, 16, v52
	v_and_b32_e32 v39, 0xffff0000, v52
	v_pk_add_f32 v[8:9], v[40:41], v[8:9]
	v_lshlrev_b32_e32 v40, 16, v53
	v_and_b32_e32 v41, 0xffff0000, v53
	v_pk_mul_f32 v[38:39], v[38:39], s[24:25] op_sel_hi:[1,0]
	v_pk_mul_f32 v[40:41], v[40:41], s[24:25] op_sel_hi:[1,0]
	v_pk_fma_f32 v[64:65], v[6:7], 0.5, v[38:39] op_sel_hi:[1,0,1]
	v_pk_fma_f32 v[62:63], v[8:9], 0.5, v[40:41] op_sel_hi:[1,0,1]
	v_mov_b32_e32 v6, v4
	v_mov_b32_e32 v7, v64
	v_mov_b32_e32 v8, v5
	v_mov_b32_e32 v9, v65
	v_pk_add_f32 v[6:7], v[6:7], v[8:9]
	v_mov_b32_e32 v8, v2
	v_mov_b32_e32 v9, v62
	v_mov_b32_e32 v38, v3
	v_mov_b32_e32 v39, v63
	v_pk_add_f32 v[8:9], v[8:9], v[38:39]
	s_nop 0
	v_pk_add_f32 v[6:7], v[6:7], v[8:9]
	s_nop 0
	v_add_f32_e32 v6, 0, v6
	v_add_f32_e32 v68, v6, v7
	v_mov_b32_e32 v52, v218
	v_mov_b32_e32 v53, v219
	v_mov_b32_e32 v6, v138
	v_mov_b32_e32 v7, v139
	v_mov_b32_e32 v8, v140
	v_mov_b32_e32 v9, v141
	v_mov_b32_e32 v38, v160
	v_mov_b32_e32 v39, v161
	v_mov_b32_e32 v40, v162
	v_mov_b32_e32 v41, v163
	v_pk_add_f32 v[40:41], v[8:9], v[40:41]
	v_pk_add_f32 v[38:39], v[6:7], v[38:39]
	v_mov_b32_e32 v6, v178
	v_mov_b32_e32 v7, v179
	v_mov_b32_e32 v8, v180
	v_mov_b32_e32 v9, v181
	v_pk_add_f32 v[40:41], v[40:41], v[8:9]
	v_pk_add_f32 v[38:39], v[38:39], v[6:7]
	v_mov_b32_e32 v6, v194
	v_mov_b32_e32 v7, v195
	v_mov_b32_e32 v8, v196
	v_mov_b32_e32 v9, v197
	v_pk_add_f32 v[8:9], v[40:41], v[8:9]
	v_pk_add_f32 v[6:7], v[38:39], v[6:7]
	v_lshlrev_b32_e32 v38, 16, v52
	v_and_b32_e32 v39, 0xffff0000, v52
	v_lshlrev_b32_e32 v40, 16, v53
	v_and_b32_e32 v41, 0xffff0000, v53
	v_pk_mul_f32 v[38:39], v[38:39], s[24:25] op_sel_hi:[1,0]
	v_pk_mul_f32 v[40:41], v[40:41], s[24:25] op_sel_hi:[1,0]
	v_pk_fma_f32 v[60:61], v[6:7], 0.5, v[38:39] op_sel_hi:[1,0,1]
	v_pk_fma_f32 v[58:59], v[8:9], 0.5, v[40:41] op_sel_hi:[1,0,1]
	v_mov_b32_e32 v8, v60
	v_pk_mov_b32 v[6:7], v[60:61], v[58:59] op_sel:[1,0]
	v_mov_b32_e32 v9, v59
	v_pk_add_f32 v[6:7], v[6:7], v[8:9]
	s_nop 0
	v_pk_add_f32 v[70:71], v[6:7], v[6:7] op_sel:[0,1] op_sel_hi:[1,0]
	v_mov_b32_e32 v52, v220
	v_mov_b32_e32 v53, v221
	v_mov_b32_e32 v6, v142
	v_mov_b32_e32 v7, v143
	v_mov_b32_e32 v8, v144
	v_mov_b32_e32 v9, v145
	v_mov_b32_e32 v38, v164
	v_mov_b32_e32 v39, v165
	v_mov_b32_e32 v40, v166
	v_mov_b32_e32 v41, v167
	v_pk_add_f32 v[40:41], v[8:9], v[40:41]
	v_pk_add_f32 v[38:39], v[6:7], v[38:39]
	v_mov_b32_e32 v6, v182
	v_mov_b32_e32 v7, v183
	v_mov_b32_e32 v8, v184
	v_mov_b32_e32 v9, v185
	v_pk_add_f32 v[40:41], v[40:41], v[8:9]
	v_pk_add_f32 v[38:39], v[38:39], v[6:7]
	v_mov_b32_e32 v6, v210
	v_mov_b32_e32 v7, v211
	v_mov_b32_e32 v8, v212
	v_mov_b32_e32 v9, v213
	global_load_dwordx2 v[214:215], v[122:123], off offset:2048
	global_load_dwordx2 v[216:217], v[122:123], off offset:2560
	global_load_dwordx2 v[218:219], v[122:123], off offset:3072
	global_load_dwordx2 v[220:221], v[122:123], off offset:3584
	global_load_dwordx4 v[130:133], v[222:223], off
	global_load_dwordx4 v[134:137], v[222:223], off offset:1024
	global_load_dwordx4 v[138:141], v[222:223], off offset:2048
	global_load_dwordx4 v[142:145], v[222:223], off offset:3072
	global_load_dwordx4 v[146:149], v[224:225], off
	global_load_dwordx4 v[150:153], v[224:225], off offset:1024
	global_load_dwordx4 v[160:163], v[224:225], off offset:2048
	global_load_dwordx4 v[164:167], v[224:225], off offset:3072
	global_load_dwordx4 v[170:173], v[226:227], off
	global_load_dwordx4 v[174:177], v[226:227], off offset:1024
	global_load_dwordx4 v[178:181], v[226:227], off offset:2048
	global_load_dwordx4 v[182:185], v[226:227], off offset:3072
	global_load_dwordx4 v[186:189], v[228:229], off
	global_load_dwordx4 v[190:193], v[228:229], off offset:1024
	global_load_dwordx4 v[194:197], v[228:229], off offset:2048
	global_load_dwordx4 v[210:213], v[228:229], off offset:3072
	s_waitcnt vmcnt(0)
; __device__ __forceinline__ float bf_lo(unsigned w) { return __uint_as_float(w << 16); }
; __device__ __forceinline__ float bf_hi(unsigned w) { return __uint_as_float(w & 0xffff0000u); }
; __device__ __forceinline__ void ln_tail_row(bf16_t* h, const float* part, float scale, const float* g, const float* b, int lane) {
;     ...
;     for (int j = 0; j < 8; ++j) { const int c = 4 * lane + 256 * j; const u32x2 w = *(const u32x2*)(h + c);
;         f32x4 p = *(const f32x4*)(part + c);
; #pragma unroll
;         for (int q = 1; q < 4; ++q) p = p + *(const f32x4*)(part + (size_t)q * 512 * D + c);
;         const f32x4 h4 = {bf_lo(w.x), bf_hi(w.x), bf_lo(w.y), bf_hi(w.y)};
;         v[j] = h4 * ALPHA + p * scale; s += (v[j].x + v[j].y) + (v[j].z + v[j].w); }
;     const float mean = wave_sum(s) * (1.f / D); float s2 = 0.f;
	v_mov_b32_e32 v48, v214
	v_mov_b32_e32 v49, v215
	v_pk_add_f32 v[8:9], v[40:41], v[8:9]
	v_pk_add_f32 v[6:7], v[38:39], v[6:7]
	v_lshlrev_b32_e32 v38, 16, v52
	v_and_b32_e32 v39, 0xffff0000, v52
	v_lshlrev_b32_e32 v40, 16, v53
	v_and_b32_e32 v41, 0xffff0000, v53
	v_pk_mul_f32 v[38:39], v[38:39], s[24:25] op_sel_hi:[1,0]
	v_pk_mul_f32 v[40:41], v[40:41], s[24:25] op_sel_hi:[1,0]
	v_pk_fma_f32 v[56:57], v[6:7], 0.5, v[38:39] op_sel_hi:[1,0,1]
	v_pk_fma_f32 v[54:55], v[8:9], 0.5, v[40:41] op_sel_hi:[1,0,1]
	v_mov_b32_e32 v6, v130
	v_mov_b32_e32 v7, v131
	v_mov_b32_e32 v8, v132
	v_mov_b32_e32 v9, v133
	v_mov_b32_e32 v38, v146
	v_mov_b32_e32 v39, v147
	v_mov_b32_e32 v40, v148
	v_mov_b32_e32 v41, v149
	v_add_f32_e32 v44, v56, v57
	v_add_f32_e32 v46, v54, v55
	v_pk_add_f32 v[40:41], v[8:9], v[40:41]
	v_pk_add_f32 v[38:39], v[6:7], v[38:39]
	v_mov_b32_e32 v6, v170
	v_mov_b32_e32 v7, v171
	v_mov_b32_e32 v8, v172
	v_mov_b32_e32 v9, v173
	v_pk_add_f32 v[40:41], v[40:41], v[8:9]
	v_pk_add_f32 v[38:39], v[38:39], v[6:7]
	v_mov_b32_e32 v6, v186
	v_mov_b32_e32 v7, v187
	v_mov_b32_e32 v8, v188
	v_mov_b32_e32 v9, v189
	v_pk_add_f32 v[8:9], v[40:41], v[8:9]
	v_pk_add_f32 v[6:7], v[38:39], v[6:7]
	v_lshlrev_b32_e32 v38, 16, v48
	v_and_b32_e32 v39, 0xffff0000, v48
	v_lshlrev_b32_e32 v40, 16, v49
	v_and_b32_e32 v41, 0xffff0000, v49
	v_pk_mul_f32 v[38:39], v[38:39], s[24:25] op_sel_hi:[1,0]
	v_pk_mul_f32 v[40:41], v[40:41], s[24:25] op_sel_hi:[1,0]
	v_pk_fma_f32 v[52:53], v[6:7], 0.5, v[38:39] op_sel_hi:[1,0,1]
	v_pk_fma_f32 v[50:51], v[8:9], 0.5, v[40:41] op_sel_hi:[1,0,1]
	v_mov_b32_e32 v69, v52
	v_mov_b32_e32 v71, v53
	v_mov_b32_e32 v45, v50
	v_mov_b32_e32 v47, v51
	v_pk_add_f32 v[6:7], v[68:69], v[70:71]
	v_pk_add_f32 v[8:9], v[44:45], v[46:47]
	s_nop 0
	v_pk_add_f32 v[6:7], v[6:7], v[8:9]
	s_nop 0
	v_pk_add_f32 v[68:69], v[6:7], v[6:7] op_sel:[0,1] op_sel_hi:[1,0]
	v_mov_b32_e32 v42, v216
	v_mov_b32_e32 v43, v217
	v_mov_b32_e32 v6, v134
	v_mov_b32_e32 v7, v135
	v_mov_b32_e32 v8, v136
	v_mov_b32_e32 v9, v137
	v_mov_b32_e32 v38, v150
	v_mov_b32_e32 v39, v151
	v_mov_b32_e32 v40, v152
	v_mov_b32_e32 v41, v153
	v_pk_add_f32 v[40:41], v[8:9], v[40:41]
	v_pk_add_f32 v[38:39], v[6:7], v[38:39]
	v_mov_b32_e32 v6, v174
	v_mov_b32_e32 v7, v175
	v_mov_b32_e32 v8, v176
	v_mov_b32_e32 v9, v177
	v_pk_add_f32 v[40:41], v[40:41], v[8:9]
	v_pk_add_f32 v[38:39], v[38:39], v[6:7]
	v_mov_b32_e32 v6, v190
	v_mov_b32_e32 v7, v191
	v_mov_b32_e32 v8, v192
	v_mov_b32_e32 v9, v193
	v_pk_add_f32 v[8:9], v[40:41], v[8:9]
	v_pk_add_f32 v[6:7], v[38:39], v[6:7]
	v_lshlrev_b32_e32 v38, 16, v42
	v_and_b32_e32 v39, 0xffff0000, v42
	v_lshlrev_b32_e32 v40, 16, v43
	v_and_b32_e32 v41, 0xffff0000, v43
	v_pk_mul_f32 v[38:39], v[38:39], s[24:25] op_sel_hi:[1,0]
	v_pk_mul_f32 v[40:41], v[40:41], s[24:25] op_sel_hi:[1,0]
	v_pk_fma_f32 v[48:49], v[6:7], 0.5, v[38:39] op_sel_hi:[1,0,1]
	v_pk_fma_f32 v[46:47], v[8:9], 0.5, v[40:41] op_sel_hi:[1,0,1]
	v_mov_b32_e32 v8, v48
	v_pk_mov_b32 v[6:7], v[48:49], v[46:47] op_sel:[1,0]
	v_mov_b32_e32 v9, v47
	v_pk_add_f32 v[6:7], v[6:7], v[8:9]
	s_nop 0
	v_pk_add_f32 v[70:71], v[6:7], v[6:7] op_sel:[0,1] op_sel_hi:[1,0]
	v_mov_b32_e32 v42, v218
	v_mov_b32_e32 v43, v219
	v_mov_b32_e32 v6, v138
	v_mov_b32_e32 v7, v139
	v_mov_b32_e32 v8, v140
	v_mov_b32_e32 v9, v141
	v_mov_b32_e32 v38, v160
	v_mov_b32_e32 v39, v161
	v_mov_b32_e32 v40, v162
	v_mov_b32_e32 v41, v163
	v_pk_add_f32 v[40:41], v[8:9], v[40:41]
	v_pk_add_f32 v[38:39], v[6:7], v[38:39]
	v_mov_b32_e32 v6, v178
	v_mov_b32_e32 v7, v179
	v_mov_b32_e32 v8, v180
	v_mov_b32_e32 v9, v181
	v_pk_add_f32 v[40:41], v[40:41], v[8:9]
	v_pk_add_f32 v[38:39], v[38:39], v[6:7]
	v_mov_b32_e32 v6, v194
	v_mov_b32_e32 v7, v195
	v_mov_b32_e32 v8, v196
	v_mov_b32_e32 v9, v197
	v_pk_add_f32 v[8:9], v[40:41], v[8:9]
	v_pk_add_f32 v[6:7], v[38:39], v[6:7]
	v_lshlrev_b32_e32 v38, 16, v42
	v_and_b32_e32 v39, 0xffff0000, v42
	v_lshlrev_b32_e32 v40, 16, v43
	v_and_b32_e32 v41, 0xffff0000, v43
	v_pk_mul_f32 v[38:39], v[38:39], s[24:25] op_sel_hi:[1,0]
	v_pk_mul_f32 v[40:41], v[40:41], s[24:25] op_sel_hi:[1,0]
	v_pk_fma_f32 v[44:45], v[6:7], 0.5, v[38:39] op_sel_hi:[1,0,1]
	v_pk_fma_f32 v[42:43], v[8:9], 0.5, v[40:41] op_sel_hi:[1,0,1]
	v_mov_b32_e32 v88, v220
	v_mov_b32_e32 v89, v221
	v_mov_b32_e32 v6, v142
	v_mov_b32_e32 v7, v143
	v_mov_b32_e32 v8, v144
	v_mov_b32_e32 v9, v145
	v_mov_b32_e32 v38, v164
	v_mov_b32_e32 v39, v165
	v_mov_b32_e32 v40, v166
	v_mov_b32_e32 v41, v167
	v_add_f32_e32 v84, v44, v45
	v_add_f32_e32 v86, v42, v43
	v_pk_add_f32 v[40:41], v[8:9], v[40:41]
	v_pk_add_f32 v[38:39], v[6:7], v[38:39]
	v_mov_b32_e32 v6, v182
	v_mov_b32_e32 v7, v183
	v_mov_b32_e32 v8, v184
	v_mov_b32_e32 v9, v185
	v_pk_add_f32 v[40:41], v[40:41], v[8:9]
	v_pk_add_f32 v[38:39], v[38:39], v[6:7]
	v_mov_b32_e32 v6, v210
	v_mov_b32_e32 v7, v211
	v_mov_b32_e32 v8, v212
	v_mov_b32_e32 v9, v213
	v_pk_add_f32 v[8:9], v[40:41], v[8:9]
	v_pk_add_f32 v[6:7], v[38:39], v[6:7]
	v_lshlrev_b32_e32 v38, 16, v88
	v_and_b32_e32 v39, 0xffff0000, v88
	v_lshlrev_b32_e32 v40, 16, v89
	v_and_b32_e32 v41, 0xffff0000, v89
	v_pk_mul_f32 v[76:77], v[38:39], s[24:25] op_sel_hi:[1,0]
	v_pk_mul_f32 v[38:39], v[40:41], s[24:25] op_sel_hi:[1,0]
	v_pk_fma_f32 v[40:41], v[6:7], 0.5, v[76:77] op_sel_hi:[1,0,1]
	v_pk_fma_f32 v[38:39], v[8:9], 0.5, v[38:39] op_sel_hi:[1,0,1]
	v_mov_b32_e32 v69, v40
	v_mov_b32_e32 v71, v41
	v_mov_b32_e32 v85, v38
	v_mov_b32_e32 v87, v39
	v_pk_add_f32 v[6:7], v[68:69], v[70:71]
	v_pk_add_f32 v[8:9], v[84:85], v[86:87]
	s_nop 0
	v_pk_add_f32 v[6:7], v[6:7], v[8:9]
	s_nop 0
	v_add_f32_e32 v6, v6, v7
	ds_bpermute_b32 v7, v1, v6
	s_waitcnt lgkmcnt(0)
; __device__ __forceinline__ void ln_tail_row(bf16_t* h, const float* part, float scale, const float* g, const float* b, int lane) {
;     ...
;     const float mean = wave_sum(s) * (1.f / D); float s2 = 0.f;
; #pragma unroll
;     for (int j = 0; j < 8; ++j) { v[j] = v[j] - mean; s2 += (v[j].x * v[j].x + v[j].y * v[j].y) + (v[j].z * v[j].z + v[j].w * v[j].w); }
;     const float rstd = rsqrtf(wave_sum(s2) * (1.f / D) + LN_EPS);
	v_add_f32_e32 v6, v6, v7
	ds_bpermute_b32 v7, v67, v6
	s_waitcnt lgkmcnt(0)
	v_add_f32_e32 v6, v6, v7
	ds_bpermute_b32 v7, v72, v6
	s_waitcnt lgkmcnt(0)
	v_add_f32_e32 v6, v6, v7
	ds_bpermute_b32 v7, v73, v6
	s_waitcnt lgkmcnt(0)
	v_add_f32_e32 v6, v6, v7
	ds_bpermute_b32 v7, v74, v6
	s_waitcnt lgkmcnt(0)
	v_add_f32_e32 v6, v6, v7
	ds_bpermute_b32 v7, v75, v6
	s_waitcnt lgkmcnt(0)
	v_add_f32_e32 v11, v6, v7
	v_fmamk_f32 v5, v11, 0xba000000, v5
	v_fmamk_f32 v65, v11, 0xba000000, v65
	v_fmamk_f32 v3, v11, 0xba000000, v3
	v_fmac_f32_e32 v4, 0xba000000, v11
	v_fmamk_f32 v63, v11, 0xba000000, v63
	v_fmac_f32_e32 v64, 0xba000000, v11
	v_mov_b32_e32 v8, v5
	v_mov_b32_e32 v9, v65
	v_fmac_f32_e32 v2, 0xba000000, v11
	v_fmac_f32_e32 v62, 0xba000000, v11
	v_mov_b32_e32 v6, v4
	v_mov_b32_e32 v7, v64
	v_pk_mul_f32 v[8:9], v[8:9], v[8:9]
	v_mov_b32_e32 v68, v3
	v_mov_b32_e32 v69, v63
	v_pk_fma_f32 v[6:7], v[6:7], v[6:7], v[8:9]
	v_mov_b32_e32 v8, v2
	v_mov_b32_e32 v9, v62
	v_pk_mul_f32 v[68:69], v[68:69], v[68:69]
	v_fmamk_f32 v61, v11, 0xba000000, v61
	v_pk_fma_f32 v[8:9], v[8:9], v[8:9], v[68:69]
	v_fmac_f32_e32 v60, 0xba000000, v11
	v_pk_add_f32 v[6:7], v[6:7], v[8:9]
	v_fmamk_f32 v59, v11, 0xba000000, v59
	v_fmac_f32_e32 v58, 0xba000000, v11
	v_pk_add_f32 v[6:7], v[6:7], v[6:7] op_sel_hi:[0,1]
	v_pk_mul_f32 v[8:9], v[58:59], v[58:59]
	v_pk_mul_f32 v[68:69], v[60:61], v[60:61]
	v_fmac_f32_e32 v56, 0xba000000, v11
	v_pk_mov_b32 v[70:71], v[68:69], v[8:9] op_sel:[1,0]
	v_mov_b32_e32 v69, v9
	v_fmamk_f32 v57, v11, 0xba000000, v57
	v_fmac_f32_e32 v54, 0xba000000, v11
	v_mul_f32_e32 v6, v56, v56
	v_pk_add_f32 v[8:9], v[70:71], v[68:69]
	v_fmamk_f32 v55, v11, 0xba000000, v55
	v_pk_fma_f32 v[68:69], v[56:57], v[56:57], v[6:7] op_sel_hi:[1,1,0]
	v_mul_f32_e32 v6, v54, v54
	v_pk_add_f32 v[8:9], v[8:9], v[8:9] op_sel_hi:[0,1]
	v_pk_fma_f32 v[70:71], v[54:55], v[54:55], v[6:7] op_sel_hi:[1,1,0]
	v_fmamk_f32 v51, v11, 0xba000000, v51
	v_fmac_f32_e32 v50, 0xba000000, v11
	v_fmamk_f32 v53, v11, 0xba000000, v53
	v_fmac_f32_e32 v52, 0xba000000, v11
	v_mul_f32_e32 v68, v52, v52
	v_mul_f32_e32 v70, v53, v53
	v_mul_f32_e32 v8, v50, v50
	v_mul_f32_e32 v6, v51, v51
	v_pk_add_f32 v[68:69], v[68:69], v[70:71]
	v_pk_add_f32 v[6:7], v[8:9], v[6:7]
	v_fmamk_f32 v49, v11, 0xba000000, v49
	v_pk_add_f32 v[6:7], v[68:69], v[6:7]
	v_fmac_f32_e32 v48, 0xba000000, v11
	v_fmamk_f32 v47, v11, 0xba000000, v47
	v_fmac_f32_e32 v46, 0xba000000, v11
	v_pk_add_f32 v[6:7], v[6:7], v[6:7] op_sel_hi:[0,1]
	v_pk_mul_f32 v[8:9], v[46:47], v[46:47]
	v_pk_mul_f32 v[68:69], v[48:49], v[48:49]
	v_fmac_f32_e32 v44, 0xba000000, v11
	v_pk_mov_b32 v[70:71], v[68:69], v[8:9] op_sel:[1,0]
	v_mov_b32_e32 v69, v9
	v_fmamk_f32 v45, v11, 0xba000000, v45
	v_fmac_f32_e32 v42, 0xba000000, v11
	v_mul_f32_e32 v6, v44, v44
	v_pk_add_f32 v[8:9], v[70:71], v[68:69]
	v_fmamk_f32 v43, v11, 0xba000000, v43
	v_pk_fma_f32 v[68:69], v[44:45], v[44:45], v[6:7] op_sel_hi:[1,1,0]
	v_mul_f32_e32 v6, v42, v42
	v_pk_add_f32 v[8:9], v[8:9], v[8:9] op_sel_hi:[0,1]
	v_pk_fma_f32 v[70:71], v[42:43], v[42:43], v[6:7] op_sel_hi:[1,1,0]
	v_fmamk_f32 v39, v11, 0xba000000, v39
	v_fmac_f32_e32 v38, 0xba000000, v11
	v_fmamk_f32 v41, v11, 0xba000000, v41
	v_fmac_f32_e32 v40, 0xba000000, v11
	v_mul_f32_e32 v68, v40, v40
	v_mul_f32_e32 v70, v41, v41
	v_mul_f32_e32 v8, v38, v38
	v_mul_f32_e32 v6, v39, v39
	v_pk_add_f32 v[68:69], v[68:69], v[70:71]
	v_pk_add_f32 v[6:7], v[8:9], v[6:7]
	s_nop 0
	v_pk_add_f32 v[6:7], v[68:69], v[6:7]
	s_nop 0
	v_add_f32_e32 v6, v6, v7
	ds_bpermute_b32 v7, v1, v6
	s_waitcnt lgkmcnt(0)
	v_add_f32_e32 v6, v6, v7
	ds_bpermute_b32 v7, v67, v6
	s_waitcnt lgkmcnt(0)
	v_add_f32_e32 v6, v6, v7
	ds_bpermute_b32 v7, v72, v6
	s_waitcnt lgkmcnt(0)
	v_add_f32_e32 v6, v6, v7
	ds_bpermute_b32 v7, v73, v6
	s_waitcnt lgkmcnt(0)
	v_add_f32_e32 v6, v6, v7
	ds_bpermute_b32 v7, v74, v6
	s_waitcnt lgkmcnt(0)
	v_add_f32_e32 v6, v6, v7
	ds_bpermute_b32 v7, v75, v6
	s_waitcnt lgkmcnt(0)
; __device__ __forceinline__ unsigned cvt_pk_bf16(float lo, float hi) { unsigned r; asm volatile("v_cvt_pk_bf16_f32 %0, %1, %2" : "=v"(r) : "v"(lo), "v"(hi)); return r; }
; __device__ __forceinline__ void ln_tail_row(bf16_t* h, const float* part, float scale, const float* g, const float* b, int lane) {
;     ...
;     const float rstd = rsqrtf(wave_sum(s2) * (1.f / D) + LN_EPS);
; #pragma unroll
;     for (int j = 0; j < 8; ++j) { const int c = 4 * lane + 256 * j; const f32x4 y = v[j] * rstd * *(const f32x4*)(g + c) + *(const f32x4*)(b + c);
;         u32x2 w; w.x = cvt_pk_bf16(y.x, y.y); w.y = cvt_pk_bf16(y.z, y.w); *(u32x2*)(h + c) = w; }
	v_add_f32_e32 v6, v6, v7
	v_fmamk_f32 v6, v6, 0x3a000000, v154
	v_cmp_gt_f32_e32 vcc, s73, v6
	v_mul_f32_e32 v7, 0x4b800000, v6
	s_nop 0
	v_cndmask_b32_e32 v6, v6, v7, vcc
	v_rsq_f32_e32 v6, v6
	s_nop 0
	v_mul_f32_e32 v7, 0x45800000, v6
	v_cndmask_b32_e32 v66, v6, v7, vcc
	v_pk_mul_f32 v[68:69], v[4:5], v[66:67] op_sel_hi:[1,0]
	v_pk_mul_f32 v[70:71], v[2:3], v[66:67] op_sel_hi:[1,0]
	ds_read_b128 v[2:5], v126
	ds_read_b128 v[6:9], v126 offset:8192
	v_pk_mul_f32 v[64:65], v[64:65], v[66:67] op_sel_hi:[1,0]
	v_pk_mul_f32 v[62:63], v[62:63], v[66:67] op_sel_hi:[1,0]
	v_pk_mul_f32 v[60:61], v[60:61], v[66:67] op_sel_hi:[1,0]
	v_pk_mul_f32 v[58:59], v[58:59], v[66:67] op_sel_hi:[1,0]
	v_pk_mul_f32 v[56:57], v[56:57], v[66:67] op_sel_hi:[1,0]
	v_pk_mul_f32 v[54:55], v[54:55], v[66:67] op_sel_hi:[1,0]
	v_pk_mul_f32 v[52:53], v[52:53], v[66:67] op_sel_hi:[1,0]
	v_pk_mul_f32 v[50:51], v[50:51], v[66:67] op_sel_hi:[1,0]
	v_pk_mul_f32 v[48:49], v[48:49], v[66:67] op_sel_hi:[1,0]
	v_pk_mul_f32 v[46:47], v[46:47], v[66:67] op_sel_hi:[1,0]
	v_pk_mul_f32 v[44:45], v[44:45], v[66:67] op_sel_hi:[1,0]
	v_pk_mul_f32 v[42:43], v[42:43], v[66:67] op_sel_hi:[1,0]
	v_pk_mul_f32 v[40:41], v[40:41], v[66:67] op_sel_hi:[1,0]
	v_cmp_lt_i32_e32 vcc, s16, v10
	v_pk_mul_f32 v[38:39], v[38:39], v[66:67] op_sel_hi:[1,0]
	s_or_b64 s[12:13], vcc, s[12:13]
	s_waitcnt lgkmcnt(0)
	v_pk_fma_f32 v[2:3], v[2:3], v[68:69], v[6:7]
	v_pk_fma_f32 v[4:5], v[4:5], v[70:71], v[8:9]
	v_cvt_pk_bf16_f32 v2, v2, v3
	s_nop 0
	v_cvt_pk_bf16_f32 v3, v4, v5
	global_store_dwordx2 v[36:37], v[2:3], off
	s_nop 1
	ds_read_b128 v[2:5], v126 offset:1024
	s_nop 0
	ds_read_b128 v[6:9], v126 offset:9216
	s_waitcnt lgkmcnt(0)
	v_pk_fma_f32 v[2:3], v[2:3], v[64:65], v[6:7]
	v_pk_fma_f32 v[4:5], v[4:5], v[62:63], v[8:9]
	v_cvt_pk_bf16_f32 v2, v2, v3
	s_nop 0
	v_cvt_pk_bf16_f32 v3, v4, v5
	global_store_dwordx2 v[36:37], v[2:3], off offset:512
	s_nop 1
	ds_read_b128 v[2:5], v126 offset:2048
	s_nop 0
	ds_read_b128 v[6:9], v126 offset:10240
	s_waitcnt lgkmcnt(0)
	v_pk_fma_f32 v[2:3], v[2:3], v[60:61], v[6:7]
	v_pk_fma_f32 v[4:5], v[4:5], v[58:59], v[8:9]
	v_cvt_pk_bf16_f32 v2, v2, v3
	s_nop 0
	v_cvt_pk_bf16_f32 v3, v4, v5
	global_store_dwordx2 v[36:37], v[2:3], off offset:1024
	s_nop 1
	ds_read_b128 v[2:5], v126 offset:3072
	s_nop 0
	ds_read_b128 v[6:9], v126 offset:11264
	s_waitcnt lgkmcnt(0)
	v_pk_fma_f32 v[2:3], v[2:3], v[56:57], v[6:7]
	v_pk_fma_f32 v[4:5], v[4:5], v[54:55], v[8:9]
	v_cvt_pk_bf16_f32 v2, v2, v3
	s_nop 0
	v_cvt_pk_bf16_f32 v3, v4, v5
	global_store_dwordx2 v[36:37], v[2:3], off offset:1536
	s_nop 1
	ds_read_b128 v[2:5], v126 offset:4096
	s_nop 0
	ds_read_b128 v[6:9], v126 offset:12288
	s_waitcnt lgkmcnt(0)
	v_pk_fma_f32 v[2:3], v[2:3], v[52:53], v[6:7]
	v_pk_fma_f32 v[4:5], v[4:5], v[50:51], v[8:9]
	v_cvt_pk_bf16_f32 v2, v2, v3
	s_nop 0
	v_cvt_pk_bf16_f32 v3, v4, v5
	global_store_dwordx2 v[36:37], v[2:3], off offset:2048
	s_nop 1
	ds_read_b128 v[2:5], v126 offset:5120
	s_nop 0
	ds_read_b128 v[6:9], v126 offset:13312
	s_waitcnt lgkmcnt(0)
	v_pk_fma_f32 v[2:3], v[2:3], v[48:49], v[6:7]
	v_pk_fma_f32 v[4:5], v[4:5], v[46:47], v[8:9]
	v_cvt_pk_bf16_f32 v2, v2, v3
	s_nop 0
	v_cvt_pk_bf16_f32 v3, v4, v5
	global_store_dwordx2 v[36:37], v[2:3], off offset:2560
	s_nop 1
	ds_read_b128 v[2:5], v126 offset:6144
	s_nop 0
	ds_read_b128 v[6:9], v126 offset:14336
	s_waitcnt lgkmcnt(0)
	v_pk_fma_f32 v[2:3], v[2:3], v[44:45], v[6:7]
	v_pk_fma_f32 v[4:5], v[4:5], v[42:43], v[8:9]
	v_cvt_pk_bf16_f32 v2, v2, v3
	s_nop 0
	v_cvt_pk_bf16_f32 v3, v4, v5
	global_store_dwordx2 v[36:37], v[2:3], off offset:3072
	s_nop 1
	ds_read_b128 v[2:5], v126 offset:7168
	s_nop 0
	ds_read_b128 v[6:9], v126 offset:15360
	s_waitcnt lgkmcnt(0)
	v_pk_fma_f32 v[2:3], v[40:41], v[2:3], v[6:7]
	v_pk_fma_f32 v[4:5], v[38:39], v[4:5], v[8:9]
	v_cvt_pk_bf16_f32 v2, v2, v3
	s_nop 0
	v_cvt_pk_bf16_f32 v3, v4, v5
	global_store_dwordx2 v[36:37], v[2:3], off offset:3584
	s_andn2_b64 exec, exec, s[12:13]
	s_cbranch_execnz .LBB0_428
